# phase 5: residual loads issued inside the last k-tile, next tile's first stage issued right after barrier 16
# speedup vs baseline: 1.0232x; 1.0029x over previous
; DI void gemm_out(const Params& p, char* lds) {
;     ...
;         int tid = threadIdx.x; asm volatile("" : "+v"(tid));
;         const int lane = tid & 63, wave = __builtin_amdgcn_readfirstlane(tid >> 6); const int wn = wave >> 1, wm = wave & 1; const int q = lane & 15, g = lane >> 4;
;         const int mt = tile >> 3, nt = tile & 7; const int m0 = mt * 96, n0 = nt * 128;
;         f32x4 acc[4][3];
; #pragma unroll
;         for (int a = 0; a < 4; ++a)
; #pragma unroll
;             for (int b = 0; b < 3; ++b) acc[a][b] = (f32x4){0.f, 0.f, 0.f, 0.f};
;         unsigned soffb[4], soffa[3];
; #pragma unroll
;         for (int i = 0; i < 4; ++i) { const int row = 8 * (i * 4 + wave) + (lane >> 3); const int ch = (lane & 7) ^ ((row >> 1) & 7); soffb[i] = (unsigned)(row * 1024 + ch * 8); }
; #pragma unroll
;         for (int i = 0; i < 3; ++i) { const int row = 8 * (i * 4 + wave) + (lane >> 3); const int ch = (lane & 7) ^ ((row >> 1) & 7); soffa[i] = (unsigned)(row * 1024 + ch * 8); }
;         const u16* ga = A + (size_t)m0 * 1024; const u16* gb = B + (size_t)n0 * 1024;
;     ...
;         OSTAGE(0, 0);
;         float4 xres[3][4];
; #pragma unroll
;         for (int tt = 0; tt < 3; ++tt) { const int row = m0 + wm * 48 + tt * 16 + q; const float* xr = row < NTP ? p.x_p + (size_t)row * DM : p.x_s + (size_t)(row - NTP) * DM;
; #pragma unroll
;             for (int ct = 0; ct < 4; ++ct) xres[tt][ct] = ntld4(xr + n0 + wn * 64 + ct * 16 + 4 * g); }
;         __syncthreads();
;         for (int kt = 0; kt < 16; ++kt) {
;             if (kt + 1 < 16) OSTAGE((kt + 1) & 1, kt + 1);
;             const char* sb = lds + (kt & 1) * 28672; const char* sa = sb + 16384;
; #pragma unroll
;             for (int ks = 0; ks < 2; ++ks) {
;                 bf16x8 fw[4], fx[3];
; #pragma unroll
;                 for (int ct = 0; ct < 4; ++ct) fw[ct] = *(const bf16x8*)(sb + swz(wn * 64 + ct * 16 + q, 4 * ks + g));
; #pragma unroll
;                 for (int tt = 0; tt < 3; ++tt) fx[tt] = *(const bf16x8*)(sa + swz(wm * 48 + tt * 16 + q, 4 * ks + g));
; #pragma unroll
;                 for (int ct = 0; ct < 4; ++ct)
; #pragma unroll
;                     for (int tt = 0; tt < 3; ++tt) acc[ct][tt] = __builtin_amdgcn_mfma_f32_16x16x32_bf16(fw[ct], fx[tt], acc[ct][tt], 0, 0, 0);
;             }
.Lo_tile:
	v_mov_b32_e32 v18, v0
	s_ashr_i32 s83, s82, 31
	v_readfirstlane_b32 s1, v18
	s_ashr_i32 s7, s1, 6
	s_ashr_i32 s4, s1, 7
	s_and_b32 s6, s7, 1
	v_bfe_u32 v2, v18, 3, 3
	s_lshl_b64 s[38:39], s[82:83], 11
	v_lshl_or_b32 v2, s7, 3, v2
	s_add_u32 s38, s54, s38
	v_lshrrev_b32_e32 v3, 1, v2
	s_addc_u32 s39, s55, s39
	s_ashr_i32 s1, s0, 31
	v_xor_b32_e32 v3, v3, v18
	s_lshl_b64 s[50:51], s[0:1], 11
	v_readlane_b32 s1, v236, 9
	v_lshlrev_b32_e32 v2, 10, v2
	v_lshlrev_b32_e32 v3, 3, v3
	s_add_u32 s50, s1, s50
	v_readlane_b32 s1, v236, 11
	v_and_or_b32 v74, v3, 56, v2
	s_addc_u32 s51, s1, s51
	s_lshl_b32 s1, s7, 10
	v_lshlrev_b64 v[66:67], 1, v[74:75]
	s_add_i32 s1, s1, 0
	v_add_u32_e32 v2, 0x8000, v74
	v_bfe_u32 v93, v18, 5, 1
	v_lshrrev_b32_e32 v8, 1, v18
	v_mov_b32_e32 v3, v75
	v_lshl_add_u64 v[76:77], s[38:39], 0, v[66:67]
	s_add_i32 s86, s1, 0x8000
	v_bitop3_b32 v10, v93, v8, 7 bitop3:0x78
	v_lshl_add_u64 v[8:9], v[76:77], 0, s[8:9]
	s_mov_b32 m0, s86
	v_lshl_add_u64 v[78:79], s[50:51], 0, v[66:67]
	s_add_i32 s87, s1, 0xc000
	v_lshlrev_b64 v[68:69], 1, v[2:3]
	v_add_u32_e32 v4, 0x10000, v74
	s_waitcnt vmcnt(0) lgkmcnt(0)
	s_barrier
	v_mov_b32_e32 v5, v75
	global_load_lds_dwordx4 v[8:9], off
	v_lshl_add_u64 v[8:9], v[78:79], 0, s[8:9]
	s_mov_b32 m0, s87
	v_lshl_add_u64 v[80:81], s[38:39], 0, v[68:69]
	s_add_i32 s88, s1, 0x9000
	global_load_lds_dwordx4 v[8:9], off
	v_lshl_add_u64 v[2:3], v[80:81], 0, s[8:9]
	s_mov_b32 m0, s88
	v_lshl_add_u64 v[82:83], s[50:51], 0, v[68:69]
	s_add_i32 s89, s1, 0xd000
	v_lshlrev_b64 v[70:71], 1, v[4:5]
	v_add_u32_e32 v6, 0x18000, v74
	v_mov_b32_e32 v7, v75
	global_load_lds_dwordx4 v[2:3], off
	v_lshl_add_u64 v[2:3], v[82:83], 0, s[8:9]
	s_mov_b32 m0, s89
	v_lshl_add_u64 v[84:85], s[38:39], 0, v[70:71]
	s_add_i32 s91, s1, 0xa000
	global_load_lds_dwordx4 v[2:3], off
	v_lshl_add_u64 v[2:3], v[84:85], 0, s[8:9]
	s_mov_b32 m0, s91
	v_lshl_add_u64 v[86:87], s[50:51], 0, v[70:71]
	s_add_i32 s92, s1, 0xe000
	v_lshlrev_b64 v[72:73], 1, v[6:7]
	global_load_lds_dwordx4 v[2:3], off
	v_lshl_add_u64 v[2:3], v[86:87], 0, s[8:9]
	s_mov_b32 m0, s92
	v_lshl_add_u64 v[88:89], s[38:39], 0, v[72:73]
	s_add_i32 s93, s1, 0xb000
	v_and_b32_e32 v94, 31, v18
	global_load_lds_dwordx4 v[2:3], off
	v_lshl_add_u64 v[2:3], v[88:89], 0, s[8:9]
	s_mov_b32 m0, s93
	v_lshl_add_u64 v[90:91], s[50:51], 0, v[72:73]
	s_add_i32 s94, s1, 0xf000
	s_lshl_b32 s7, s4, 13
	v_lshlrev_b32_e32 v116, 7, v94
	global_load_lds_dwordx4 v[2:3], off
	v_lshl_add_u64 v[2:3], v[90:91], 0, s[8:9]
	s_mov_b32 m0, s94
	v_lshl_add_u32 v6, v10, 4, 0
	global_load_lds_dwordx4 v[2:3], off
	v_add3_u32 v74, v6, s7, v116
	ds_read_b128 v[2:5], v74 offset:16384
	s_lshl_b32 s38, s6, 13
	v_add3_u32 v96, v6, s38, v116
	v_bfe_u32 v117, v18, 1, 3
	ds_read_b128 v[6:9], v96
	ds_read_b128 v[10:13], v96 offset:4096
	ds_read_b128 v[14:17], v74 offset:20480
	v_bitop3_b32 v18, v93, v117, 2 bitop3:0x36
	v_lshl_add_u32 v18, v18, 4, 0
	v_add3_u32 v95, v18, s7, v116
	ds_read_b128 v[50:53], v95 offset:16384
	s_waitcnt lgkmcnt(0)
	v_mfma_f32_32x32x16_bf16 v[34:49], v[6:9], v[2:5], 0
	v_add3_u32 v97, v18, s38, v116
	ds_read_b128 v[98:101], v97
	ds_read_b128 v[102:105], v97 offset:4096
	ds_read_b128 v[106:109], v95 offset:20480
	s_mov_b32 m0, s1
	s_add_i32 s39, s1, 0x5000
	s_add_i32 s50, s1, 0x2000
	s_add_i32 s51, s1, 0x6000
	s_add_i32 s83, s1, 0x3000
	v_mfma_f32_32x32x16_bf16 v[18:33], v[10:13], v[2:5], 0
	s_add_i32 s90, s1, 0x7000
	s_add_i32 s33, s33, s95
	s_waitcnt lgkmcnt(0)
	v_mfma_f32_32x32x16_bf16 v[34:49], v[98:101], v[50:53], v[34:49]
	v_mfma_f32_32x32x16_bf16 v[18:33], v[102:105], v[50:53], v[18:33]
	v_mfma_f32_32x32x16_bf16 v[50:65], v[6:9], v[14:17], 0
	v_mfma_f32_32x32x16_bf16 v[2:17], v[10:13], v[14:17], 0
	v_mfma_f32_32x32x16_bf16 v[50:65], v[98:101], v[106:109], v[50:65]
	v_bitop3_b32 v98, v93, v117, 4 bitop3:0x36
	v_lshl_add_u32 v99, v98, 4, 0
	v_add3_u32 v98, v99, s7, v116
	v_add3_u32 v99, v99, s38, v116
	v_mfma_f32_32x32x16_bf16 v[2:17], v[102:105], v[106:109], v[2:17]
	ds_read_b128 v[100:103], v98 offset:16384
	ds_read_b128 v[104:107], v99
	ds_read_b128 v[108:111], v99 offset:4096
	ds_read_b128 v[112:115], v98 offset:20480
	s_waitcnt lgkmcnt(0)
	v_mfma_f32_32x32x16_bf16 v[34:49], v[104:107], v[100:103], v[34:49]
	v_mfma_f32_32x32x16_bf16 v[18:33], v[108:111], v[100:103], v[18:33]
	v_bitop3_b32 v100, v93, v117, 6 bitop3:0x36
	v_lshl_add_u32 v101, v100, 4, 0
	v_add3_u32 v100, v101, s7, v116
	v_add3_u32 v101, v101, s38, v116
	s_add_i32 s7, s1, 0x4000
	s_add_i32 s38, s1, 0x1000
	s_cmpk_gt_i32 s33, 0x41f
	v_mfma_f32_32x32x16_bf16 v[50:65], v[104:107], v[112:115], v[50:65]
	v_mfma_f32_32x32x16_bf16 v[2:17], v[108:111], v[112:115], v[2:17]
	ds_read_b128 v[238:241], v100 offset:16384
	ds_read_b128 v[242:245], v101
	ds_read_b128 v[246:249], v101 offset:4096
	ds_read_b128 v[250:253], v100 offset:20480
	s_waitcnt vmcnt(0) lgkmcnt(0)
	s_barrier
; DI void gemm_out(const Params& p, char* lds) {
;     ...
;         for (int kt = 0; kt < 16; ++kt) {
;             if (kt + 1 < 16) OSTAGE((kt + 1) & 1, kt + 1);
;             const char* sb = lds + (kt & 1) * 28672; const char* sa = sb + 16384;
; #pragma unroll
;             for (int ks = 0; ks < 2; ++ks) {
;                 bf16x8 fw[4], fx[3];
; #pragma unroll
;                 for (int ct = 0; ct < 4; ++ct) fw[ct] = *(const bf16x8*)(sb + swz(wn * 64 + ct * 16 + q, 4 * ks + g));
; #pragma unroll
;                 for (int tt = 0; tt < 3; ++tt) fx[tt] = *(const bf16x8*)(sa + swz(wm * 48 + tt * 16 + q, 4 * ks + g));
; #pragma unroll
;                 for (int ct = 0; ct < 4; ++ct)
; #pragma unroll
;                     for (int tt = 0; tt < 3; ++tt) acc[ct][tt] = __builtin_amdgcn_mfma_f32_16x16x32_bf16(fw[ct], fx[tt], acc[ct][tt], 0, 0, 0);
;             }
;             __syncthreads();
;         }
	ds_read_b128 v[102:105], v74 offset:49152
	ds_read_b128 v[106:109], v96 offset:32768
	ds_read_b128 v[110:113], v96 offset:36864
	ds_read_b128 v[114:117], v74 offset:53248
	v_mfma_f32_32x32x16_bf16 v[34:49], v[242:245], v[238:241], v[34:49]
	v_mfma_f32_32x32x16_bf16 v[18:33], v[246:249], v[238:241], v[18:33]
	v_lshl_add_u64 v[254:255], v[76:77], 0, s[10:11]
	global_load_lds_dwordx4 v[254:255], off
	v_lshl_add_u64 v[254:255], v[78:79], 0, s[10:11]
	s_mov_b32 m0, s7
	s_nop 0
	global_load_lds_dwordx4 v[254:255], off
	v_lshl_add_u64 v[254:255], v[80:81], 0, s[10:11]
	s_mov_b32 m0, s38
	v_mfma_f32_32x32x16_bf16 v[50:65], v[242:245], v[250:253], v[50:65]
	global_load_lds_dwordx4 v[254:255], off
	v_lshl_add_u64 v[254:255], v[82:83], 0, s[10:11]
	s_mov_b32 m0, s39
	s_nop 0
	global_load_lds_dwordx4 v[254:255], off
	v_lshl_add_u64 v[254:255], v[84:85], 0, s[10:11]
	s_mov_b32 m0, s50
	v_mfma_f32_32x32x16_bf16 v[2:17], v[246:249], v[250:253], v[2:17]
	global_load_lds_dwordx4 v[254:255], off
	v_lshl_add_u64 v[254:255], v[86:87], 0, s[10:11]
	s_mov_b32 m0, s51
	s_nop 0
	global_load_lds_dwordx4 v[254:255], off
	v_lshl_add_u64 v[254:255], v[88:89], 0, s[10:11]
	s_mov_b32 m0, s83
	s_nop 0
	global_load_lds_dwordx4 v[254:255], off
	v_lshl_add_u64 v[254:255], v[90:91], 0, s[10:11]
	s_mov_b32 m0, s90
	s_nop 0
	global_load_lds_dwordx4 v[254:255], off
	s_waitcnt lgkmcnt(0)
	ds_read_b128 v[238:241], v95 offset:49152
	ds_read_b128 v[242:245], v97 offset:32768
	ds_read_b128 v[246:249], v97 offset:36864
	ds_read_b128 v[250:253], v95 offset:53248
	v_mfma_f32_32x32x16_bf16 v[34:49], v[106:109], v[102:105], v[34:49]
	s_mov_b32 m0, s86
	v_mfma_f32_32x32x16_bf16 v[18:33], v[110:113], v[102:105], v[18:33]
	v_mfma_f32_32x32x16_bf16 v[50:65], v[106:109], v[114:117], v[50:65]
	v_mfma_f32_32x32x16_bf16 v[2:17], v[110:113], v[114:117], v[2:17]
	s_waitcnt lgkmcnt(0)
	ds_read_b128 v[102:105], v98 offset:49152
	ds_read_b128 v[106:109], v99 offset:32768
	ds_read_b128 v[110:113], v99 offset:36864
	ds_read_b128 v[114:117], v98 offset:53248
	v_mfma_f32_32x32x16_bf16 v[34:49], v[242:245], v[238:241], v[34:49]
	v_mfma_f32_32x32x16_bf16 v[18:33], v[246:249], v[238:241], v[18:33]
	v_mfma_f32_32x32x16_bf16 v[50:65], v[242:245], v[250:253], v[50:65]
	v_mfma_f32_32x32x16_bf16 v[2:17], v[246:249], v[250:253], v[2:17]
	s_waitcnt lgkmcnt(0)
	ds_read_b128 v[238:241], v100 offset:49152
	ds_read_b128 v[242:245], v101 offset:32768
	ds_read_b128 v[246:249], v101 offset:36864
	ds_read_b128 v[250:253], v100 offset:53248
	v_mfma_f32_32x32x16_bf16 v[34:49], v[106:109], v[102:105], v[34:49]
	v_mfma_f32_32x32x16_bf16 v[18:33], v[110:113], v[102:105], v[18:33]
	v_mfma_f32_32x32x16_bf16 v[50:65], v[106:109], v[114:117], v[50:65]
	v_mfma_f32_32x32x16_bf16 v[2:17], v[110:113], v[114:117], v[2:17]
	s_waitcnt vmcnt(0) lgkmcnt(0)
	s_barrier
	ds_read_b128 v[102:105], v74 offset:16384
	ds_read_b128 v[106:109], v96
	ds_read_b128 v[110:113], v96 offset:4096
	ds_read_b128 v[114:117], v74 offset:20480
	v_mfma_f32_32x32x16_bf16 v[34:49], v[242:245], v[238:241], v[34:49]
	v_mfma_f32_32x32x16_bf16 v[18:33], v[246:249], v[238:241], v[18:33]
	v_lshl_add_u64 v[254:255], v[76:77], 0, s[12:13]
	global_load_lds_dwordx4 v[254:255], off
	v_lshl_add_u64 v[254:255], v[78:79], 0, s[12:13]
	s_mov_b32 m0, s87
	s_nop 0
	global_load_lds_dwordx4 v[254:255], off
	v_lshl_add_u64 v[254:255], v[80:81], 0, s[12:13]
	s_mov_b32 m0, s88
	v_mfma_f32_32x32x16_bf16 v[50:65], v[242:245], v[250:253], v[50:65]
	global_load_lds_dwordx4 v[254:255], off
	v_lshl_add_u64 v[254:255], v[82:83], 0, s[12:13]
	s_mov_b32 m0, s89
	s_nop 0
	global_load_lds_dwordx4 v[254:255], off
	v_lshl_add_u64 v[254:255], v[84:85], 0, s[12:13]
	s_mov_b32 m0, s91
	v_mfma_f32_32x32x16_bf16 v[2:17], v[246:249], v[250:253], v[2:17]
	global_load_lds_dwordx4 v[254:255], off
	v_lshl_add_u64 v[254:255], v[86:87], 0, s[12:13]
	s_mov_b32 m0, s92
	s_nop 0
	global_load_lds_dwordx4 v[254:255], off
	v_lshl_add_u64 v[254:255], v[88:89], 0, s[12:13]
	s_mov_b32 m0, s93
	s_nop 0
	global_load_lds_dwordx4 v[254:255], off
	v_lshl_add_u64 v[254:255], v[90:91], 0, s[12:13]
	s_mov_b32 m0, s94
	s_nop 0
	global_load_lds_dwordx4 v[254:255], off
	s_waitcnt lgkmcnt(0)
	ds_read_b128 v[238:241], v95 offset:16384
	ds_read_b128 v[242:245], v97
	ds_read_b128 v[246:249], v97 offset:4096
	ds_read_b128 v[250:253], v95 offset:20480
	v_mfma_f32_32x32x16_bf16 v[34:49], v[106:109], v[102:105], v[34:49]
	s_mov_b32 m0, s1
	v_mfma_f32_32x32x16_bf16 v[18:33], v[110:113], v[102:105], v[18:33]
	v_mfma_f32_32x32x16_bf16 v[50:65], v[106:109], v[114:117], v[50:65]
	v_mfma_f32_32x32x16_bf16 v[2:17], v[110:113], v[114:117], v[2:17]
	s_waitcnt lgkmcnt(0)
	ds_read_b128 v[102:105], v98 offset:16384
	ds_read_b128 v[106:109], v99
	ds_read_b128 v[110:113], v99 offset:4096
	ds_read_b128 v[114:117], v98 offset:20480
	v_mfma_f32_32x32x16_bf16 v[34:49], v[242:245], v[238:241], v[34:49]
	v_mfma_f32_32x32x16_bf16 v[18:33], v[246:249], v[238:241], v[18:33]
	v_mfma_f32_32x32x16_bf16 v[50:65], v[242:245], v[250:253], v[50:65]
	v_mfma_f32_32x32x16_bf16 v[2:17], v[246:249], v[250:253], v[2:17]
	s_waitcnt lgkmcnt(0)
	ds_read_b128 v[238:241], v100 offset:16384
	ds_read_b128 v[242:245], v101
	ds_read_b128 v[246:249], v101 offset:4096
	ds_read_b128 v[250:253], v100 offset:20480
	v_mfma_f32_32x32x16_bf16 v[34:49], v[106:109], v[102:105], v[34:49]
	v_mfma_f32_32x32x16_bf16 v[18:33], v[110:113], v[102:105], v[18:33]
	v_mfma_f32_32x32x16_bf16 v[50:65], v[106:109], v[114:117], v[50:65]
	v_mfma_f32_32x32x16_bf16 v[2:17], v[110:113], v[114:117], v[2:17]
	s_waitcnt vmcnt(0) lgkmcnt(0)
	s_barrier
; DI void gemm_out(const Params& p, char* lds) {
;     ...
;         for (int kt = 0; kt < 16; ++kt) {
;             if (kt + 1 < 16) OSTAGE((kt + 1) & 1, kt + 1);
;             const char* sb = lds + (kt & 1) * 28672; const char* sa = sb + 16384;
; #pragma unroll
;             for (int ks = 0; ks < 2; ++ks) {
;                 bf16x8 fw[4], fx[3];
; #pragma unroll
;                 for (int ct = 0; ct < 4; ++ct) fw[ct] = *(const bf16x8*)(sb + swz(wn * 64 + ct * 16 + q, 4 * ks + g));
; #pragma unroll
;                 for (int tt = 0; tt < 3; ++tt) fx[tt] = *(const bf16x8*)(sa + swz(wm * 48 + tt * 16 + q, 4 * ks + g));
; #pragma unroll
;                 for (int ct = 0; ct < 4; ++ct)
; #pragma unroll
;                     for (int tt = 0; tt < 3; ++tt) acc[ct][tt] = __builtin_amdgcn_mfma_f32_16x16x32_bf16(fw[ct], fx[tt], acc[ct][tt], 0, 0, 0);
;             }
;             __syncthreads();
;         }
	ds_read_b128 v[102:105], v74 offset:49152
	ds_read_b128 v[106:109], v96 offset:32768
	ds_read_b128 v[110:113], v96 offset:36864
	ds_read_b128 v[114:117], v74 offset:53248
	v_mfma_f32_32x32x16_bf16 v[34:49], v[242:245], v[238:241], v[34:49]
	v_mfma_f32_32x32x16_bf16 v[18:33], v[246:249], v[238:241], v[18:33]
	v_lshl_add_u64 v[254:255], v[76:77], 0, s[14:15]
	global_load_lds_dwordx4 v[254:255], off
	v_lshl_add_u64 v[254:255], v[78:79], 0, s[14:15]
	s_mov_b32 m0, s7
	s_nop 0
	global_load_lds_dwordx4 v[254:255], off
	v_lshl_add_u64 v[254:255], v[80:81], 0, s[14:15]
	s_mov_b32 m0, s38
	v_mfma_f32_32x32x16_bf16 v[50:65], v[242:245], v[250:253], v[50:65]
	global_load_lds_dwordx4 v[254:255], off
	v_lshl_add_u64 v[254:255], v[82:83], 0, s[14:15]
	s_mov_b32 m0, s39
	s_nop 0
	global_load_lds_dwordx4 v[254:255], off
	v_lshl_add_u64 v[254:255], v[84:85], 0, s[14:15]
	s_mov_b32 m0, s50
	v_mfma_f32_32x32x16_bf16 v[2:17], v[246:249], v[250:253], v[2:17]
	global_load_lds_dwordx4 v[254:255], off
	v_lshl_add_u64 v[254:255], v[86:87], 0, s[14:15]
	s_mov_b32 m0, s51
	s_nop 0
	global_load_lds_dwordx4 v[254:255], off
	v_lshl_add_u64 v[254:255], v[88:89], 0, s[14:15]
	s_mov_b32 m0, s83
	s_nop 0
	global_load_lds_dwordx4 v[254:255], off
	v_lshl_add_u64 v[254:255], v[90:91], 0, s[14:15]
	s_mov_b32 m0, s90
	s_nop 0
	global_load_lds_dwordx4 v[254:255], off
	s_waitcnt lgkmcnt(0)
	ds_read_b128 v[238:241], v95 offset:49152
	ds_read_b128 v[242:245], v97 offset:32768
	ds_read_b128 v[246:249], v97 offset:36864
	ds_read_b128 v[250:253], v95 offset:53248
	v_mfma_f32_32x32x16_bf16 v[34:49], v[106:109], v[102:105], v[34:49]
	s_mov_b32 m0, s86
	v_mfma_f32_32x32x16_bf16 v[18:33], v[110:113], v[102:105], v[18:33]
	v_mfma_f32_32x32x16_bf16 v[50:65], v[106:109], v[114:117], v[50:65]
	v_mfma_f32_32x32x16_bf16 v[2:17], v[110:113], v[114:117], v[2:17]
	s_waitcnt lgkmcnt(0)
	ds_read_b128 v[102:105], v98 offset:49152
	ds_read_b128 v[106:109], v99 offset:32768
	ds_read_b128 v[110:113], v99 offset:36864
	ds_read_b128 v[114:117], v98 offset:53248
	v_mfma_f32_32x32x16_bf16 v[34:49], v[242:245], v[238:241], v[34:49]
	v_mfma_f32_32x32x16_bf16 v[18:33], v[246:249], v[238:241], v[18:33]
	v_mfma_f32_32x32x16_bf16 v[50:65], v[242:245], v[250:253], v[50:65]
	v_mfma_f32_32x32x16_bf16 v[2:17], v[246:249], v[250:253], v[2:17]
	s_waitcnt lgkmcnt(0)
	ds_read_b128 v[238:241], v100 offset:49152
	ds_read_b128 v[242:245], v101 offset:32768
	ds_read_b128 v[246:249], v101 offset:36864
	ds_read_b128 v[250:253], v100 offset:53248
	v_mfma_f32_32x32x16_bf16 v[34:49], v[106:109], v[102:105], v[34:49]
	v_mfma_f32_32x32x16_bf16 v[18:33], v[110:113], v[102:105], v[18:33]
	v_mfma_f32_32x32x16_bf16 v[50:65], v[106:109], v[114:117], v[50:65]
	v_mfma_f32_32x32x16_bf16 v[2:17], v[110:113], v[114:117], v[2:17]
	s_waitcnt vmcnt(0) lgkmcnt(0)
	s_barrier
	ds_read_b128 v[102:105], v74 offset:16384
	ds_read_b128 v[106:109], v96
	ds_read_b128 v[110:113], v96 offset:4096
	ds_read_b128 v[114:117], v74 offset:20480
	v_mfma_f32_32x32x16_bf16 v[34:49], v[242:245], v[238:241], v[34:49]
	v_mfma_f32_32x32x16_bf16 v[18:33], v[246:249], v[238:241], v[18:33]
	v_lshl_add_u64 v[254:255], v[76:77], 0, s[16:17]
	global_load_lds_dwordx4 v[254:255], off
	v_lshl_add_u64 v[254:255], v[78:79], 0, s[16:17]
	s_mov_b32 m0, s87
	s_nop 0
	global_load_lds_dwordx4 v[254:255], off
	v_lshl_add_u64 v[254:255], v[80:81], 0, s[16:17]
	s_mov_b32 m0, s88
	v_mfma_f32_32x32x16_bf16 v[50:65], v[242:245], v[250:253], v[50:65]
	global_load_lds_dwordx4 v[254:255], off
	v_lshl_add_u64 v[254:255], v[82:83], 0, s[16:17]
	s_mov_b32 m0, s89
	s_nop 0
	global_load_lds_dwordx4 v[254:255], off
	v_lshl_add_u64 v[254:255], v[84:85], 0, s[16:17]
	s_mov_b32 m0, s91
	v_mfma_f32_32x32x16_bf16 v[2:17], v[246:249], v[250:253], v[2:17]
	global_load_lds_dwordx4 v[254:255], off
	v_lshl_add_u64 v[254:255], v[86:87], 0, s[16:17]
	s_mov_b32 m0, s92
	s_nop 0
	global_load_lds_dwordx4 v[254:255], off
	v_lshl_add_u64 v[254:255], v[88:89], 0, s[16:17]
	s_mov_b32 m0, s93
	s_nop 0
	global_load_lds_dwordx4 v[254:255], off
	v_lshl_add_u64 v[254:255], v[90:91], 0, s[16:17]
	s_mov_b32 m0, s94
	s_nop 0
	global_load_lds_dwordx4 v[254:255], off
	s_waitcnt lgkmcnt(0)
	ds_read_b128 v[238:241], v95 offset:16384
	ds_read_b128 v[242:245], v97
	ds_read_b128 v[246:249], v97 offset:4096
	ds_read_b128 v[250:253], v95 offset:20480
	v_mfma_f32_32x32x16_bf16 v[34:49], v[106:109], v[102:105], v[34:49]
	s_mov_b32 m0, s1
	v_mfma_f32_32x32x16_bf16 v[18:33], v[110:113], v[102:105], v[18:33]
	v_mfma_f32_32x32x16_bf16 v[50:65], v[106:109], v[114:117], v[50:65]
	v_mfma_f32_32x32x16_bf16 v[2:17], v[110:113], v[114:117], v[2:17]
	s_waitcnt lgkmcnt(0)
	ds_read_b128 v[102:105], v98 offset:16384
	ds_read_b128 v[106:109], v99
	ds_read_b128 v[110:113], v99 offset:4096
	ds_read_b128 v[114:117], v98 offset:20480
	v_mfma_f32_32x32x16_bf16 v[34:49], v[242:245], v[238:241], v[34:49]
	v_mfma_f32_32x32x16_bf16 v[18:33], v[246:249], v[238:241], v[18:33]
	v_mfma_f32_32x32x16_bf16 v[50:65], v[242:245], v[250:253], v[50:65]
	v_mfma_f32_32x32x16_bf16 v[2:17], v[246:249], v[250:253], v[2:17]
	s_waitcnt lgkmcnt(0)
	ds_read_b128 v[238:241], v100 offset:16384
	ds_read_b128 v[242:245], v101
	ds_read_b128 v[246:249], v101 offset:4096
	ds_read_b128 v[250:253], v100 offset:20480
	v_mfma_f32_32x32x16_bf16 v[34:49], v[106:109], v[102:105], v[34:49]
	v_mfma_f32_32x32x16_bf16 v[18:33], v[110:113], v[102:105], v[18:33]
	v_mfma_f32_32x32x16_bf16 v[50:65], v[106:109], v[114:117], v[50:65]
	v_mfma_f32_32x32x16_bf16 v[2:17], v[110:113], v[114:117], v[2:17]
	s_waitcnt vmcnt(0) lgkmcnt(0)
	s_barrier
; DI void gemm_out(const Params& p, char* lds) {
;     ...
;         for (int kt = 0; kt < 16; ++kt) {
;             if (kt + 1 < 16) OSTAGE((kt + 1) & 1, kt + 1);
;             const char* sb = lds + (kt & 1) * 28672; const char* sa = sb + 16384;
; #pragma unroll
;             for (int ks = 0; ks < 2; ++ks) {
;                 bf16x8 fw[4], fx[3];
; #pragma unroll
;                 for (int ct = 0; ct < 4; ++ct) fw[ct] = *(const bf16x8*)(sb + swz(wn * 64 + ct * 16 + q, 4 * ks + g));
; #pragma unroll
;                 for (int tt = 0; tt < 3; ++tt) fx[tt] = *(const bf16x8*)(sa + swz(wm * 48 + tt * 16 + q, 4 * ks + g));
; #pragma unroll
;                 for (int ct = 0; ct < 4; ++ct)
; #pragma unroll
;                     for (int tt = 0; tt < 3; ++tt) acc[ct][tt] = __builtin_amdgcn_mfma_f32_16x16x32_bf16(fw[ct], fx[tt], acc[ct][tt], 0, 0, 0);
;             }
;             __syncthreads();
;         }
	ds_read_b128 v[102:105], v74 offset:49152
	ds_read_b128 v[106:109], v96 offset:32768
	ds_read_b128 v[110:113], v96 offset:36864
	ds_read_b128 v[114:117], v74 offset:53248
	v_mfma_f32_32x32x16_bf16 v[34:49], v[242:245], v[238:241], v[34:49]
	v_mfma_f32_32x32x16_bf16 v[18:33], v[246:249], v[238:241], v[18:33]
	v_lshl_add_u64 v[254:255], v[76:77], 0, s[18:19]
	global_load_lds_dwordx4 v[254:255], off
	v_lshl_add_u64 v[254:255], v[78:79], 0, s[18:19]
	s_mov_b32 m0, s7
	s_nop 0
	global_load_lds_dwordx4 v[254:255], off
	v_lshl_add_u64 v[254:255], v[80:81], 0, s[18:19]
	s_mov_b32 m0, s38
	v_mfma_f32_32x32x16_bf16 v[50:65], v[242:245], v[250:253], v[50:65]
	global_load_lds_dwordx4 v[254:255], off
	v_lshl_add_u64 v[254:255], v[82:83], 0, s[18:19]
	s_mov_b32 m0, s39
	s_nop 0
	global_load_lds_dwordx4 v[254:255], off
	v_lshl_add_u64 v[254:255], v[84:85], 0, s[18:19]
	s_mov_b32 m0, s50
	v_mfma_f32_32x32x16_bf16 v[2:17], v[246:249], v[250:253], v[2:17]
	global_load_lds_dwordx4 v[254:255], off
	v_lshl_add_u64 v[254:255], v[86:87], 0, s[18:19]
	s_mov_b32 m0, s51
	s_nop 0
	global_load_lds_dwordx4 v[254:255], off
	v_lshl_add_u64 v[254:255], v[88:89], 0, s[18:19]
	s_mov_b32 m0, s83
	s_nop 0
	global_load_lds_dwordx4 v[254:255], off
	v_lshl_add_u64 v[254:255], v[90:91], 0, s[18:19]
	s_mov_b32 m0, s90
	s_nop 0
	global_load_lds_dwordx4 v[254:255], off
	s_waitcnt lgkmcnt(0)
	ds_read_b128 v[238:241], v95 offset:49152
	ds_read_b128 v[242:245], v97 offset:32768
	ds_read_b128 v[246:249], v97 offset:36864
	ds_read_b128 v[250:253], v95 offset:53248
	v_mfma_f32_32x32x16_bf16 v[34:49], v[106:109], v[102:105], v[34:49]
	s_mov_b32 m0, s86
	v_mfma_f32_32x32x16_bf16 v[18:33], v[110:113], v[102:105], v[18:33]
	v_mfma_f32_32x32x16_bf16 v[50:65], v[106:109], v[114:117], v[50:65]
	v_mfma_f32_32x32x16_bf16 v[2:17], v[110:113], v[114:117], v[2:17]
	s_waitcnt lgkmcnt(0)
	ds_read_b128 v[102:105], v98 offset:49152
	ds_read_b128 v[106:109], v99 offset:32768
	ds_read_b128 v[110:113], v99 offset:36864
	ds_read_b128 v[114:117], v98 offset:53248
	v_mfma_f32_32x32x16_bf16 v[34:49], v[242:245], v[238:241], v[34:49]
	v_mfma_f32_32x32x16_bf16 v[18:33], v[246:249], v[238:241], v[18:33]
	v_mfma_f32_32x32x16_bf16 v[50:65], v[242:245], v[250:253], v[50:65]
	v_mfma_f32_32x32x16_bf16 v[2:17], v[246:249], v[250:253], v[2:17]
	s_waitcnt lgkmcnt(0)
	ds_read_b128 v[238:241], v100 offset:49152
	ds_read_b128 v[242:245], v101 offset:32768
	ds_read_b128 v[246:249], v101 offset:36864
	ds_read_b128 v[250:253], v100 offset:53248
	v_mfma_f32_32x32x16_bf16 v[34:49], v[106:109], v[102:105], v[34:49]
	v_mfma_f32_32x32x16_bf16 v[18:33], v[110:113], v[102:105], v[18:33]
	v_mfma_f32_32x32x16_bf16 v[50:65], v[106:109], v[114:117], v[50:65]
	v_mfma_f32_32x32x16_bf16 v[2:17], v[110:113], v[114:117], v[2:17]
	s_waitcnt vmcnt(0) lgkmcnt(0)
	s_barrier
	ds_read_b128 v[102:105], v74 offset:16384
	ds_read_b128 v[106:109], v96
	ds_read_b128 v[110:113], v96 offset:4096
	ds_read_b128 v[114:117], v74 offset:20480
	v_mfma_f32_32x32x16_bf16 v[34:49], v[242:245], v[238:241], v[34:49]
	v_mfma_f32_32x32x16_bf16 v[18:33], v[246:249], v[238:241], v[18:33]
	v_lshl_add_u64 v[254:255], v[76:77], 0, s[20:21]
	global_load_lds_dwordx4 v[254:255], off
	v_lshl_add_u64 v[254:255], v[78:79], 0, s[20:21]
	s_mov_b32 m0, s87
	s_nop 0
	global_load_lds_dwordx4 v[254:255], off
	v_lshl_add_u64 v[254:255], v[80:81], 0, s[20:21]
	s_mov_b32 m0, s88
	v_mfma_f32_32x32x16_bf16 v[50:65], v[242:245], v[250:253], v[50:65]
	global_load_lds_dwordx4 v[254:255], off
	v_lshl_add_u64 v[254:255], v[82:83], 0, s[20:21]
	s_mov_b32 m0, s89
	s_nop 0
	global_load_lds_dwordx4 v[254:255], off
	v_lshl_add_u64 v[254:255], v[84:85], 0, s[20:21]
	s_mov_b32 m0, s91
	v_mfma_f32_32x32x16_bf16 v[2:17], v[246:249], v[250:253], v[2:17]
	global_load_lds_dwordx4 v[254:255], off
	v_lshl_add_u64 v[254:255], v[86:87], 0, s[20:21]
	s_mov_b32 m0, s92
	s_nop 0
	global_load_lds_dwordx4 v[254:255], off
	v_lshl_add_u64 v[254:255], v[88:89], 0, s[20:21]
	s_mov_b32 m0, s93
	s_nop 0
	global_load_lds_dwordx4 v[254:255], off
	v_lshl_add_u64 v[254:255], v[90:91], 0, s[20:21]
	s_mov_b32 m0, s94
	s_nop 0
	global_load_lds_dwordx4 v[254:255], off
	s_waitcnt lgkmcnt(0)
	ds_read_b128 v[238:241], v95 offset:16384
	ds_read_b128 v[242:245], v97
	ds_read_b128 v[246:249], v97 offset:4096
	ds_read_b128 v[250:253], v95 offset:20480
	v_mfma_f32_32x32x16_bf16 v[34:49], v[106:109], v[102:105], v[34:49]
	s_mov_b32 m0, s1
	v_mfma_f32_32x32x16_bf16 v[18:33], v[110:113], v[102:105], v[18:33]
	v_mfma_f32_32x32x16_bf16 v[50:65], v[106:109], v[114:117], v[50:65]
	v_mfma_f32_32x32x16_bf16 v[2:17], v[110:113], v[114:117], v[2:17]
	s_waitcnt lgkmcnt(0)
	ds_read_b128 v[102:105], v98 offset:16384
	ds_read_b128 v[106:109], v99
	ds_read_b128 v[110:113], v99 offset:4096
	ds_read_b128 v[114:117], v98 offset:20480
	v_mfma_f32_32x32x16_bf16 v[34:49], v[242:245], v[238:241], v[34:49]
	v_mfma_f32_32x32x16_bf16 v[18:33], v[246:249], v[238:241], v[18:33]
	v_mfma_f32_32x32x16_bf16 v[50:65], v[242:245], v[250:253], v[50:65]
	v_mfma_f32_32x32x16_bf16 v[2:17], v[246:249], v[250:253], v[2:17]
	s_waitcnt lgkmcnt(0)
	ds_read_b128 v[238:241], v100 offset:16384
	ds_read_b128 v[242:245], v101
	ds_read_b128 v[246:249], v101 offset:4096
	ds_read_b128 v[250:253], v100 offset:20480
	v_mfma_f32_32x32x16_bf16 v[34:49], v[106:109], v[102:105], v[34:49]
	v_mfma_f32_32x32x16_bf16 v[18:33], v[110:113], v[102:105], v[18:33]
	v_mfma_f32_32x32x16_bf16 v[50:65], v[106:109], v[114:117], v[50:65]
	v_mfma_f32_32x32x16_bf16 v[2:17], v[110:113], v[114:117], v[2:17]
	s_waitcnt vmcnt(0) lgkmcnt(0)
	s_barrier
; DI void gemm_out(const Params& p, char* lds) {
;     ...
;         for (int kt = 0; kt < 16; ++kt) {
;             if (kt + 1 < 16) OSTAGE((kt + 1) & 1, kt + 1);
;             const char* sb = lds + (kt & 1) * 28672; const char* sa = sb + 16384;
; #pragma unroll
;             for (int ks = 0; ks < 2; ++ks) {
;                 bf16x8 fw[4], fx[3];
; #pragma unroll
;                 for (int ct = 0; ct < 4; ++ct) fw[ct] = *(const bf16x8*)(sb + swz(wn * 64 + ct * 16 + q, 4 * ks + g));
; #pragma unroll
;                 for (int tt = 0; tt < 3; ++tt) fx[tt] = *(const bf16x8*)(sa + swz(wm * 48 + tt * 16 + q, 4 * ks + g));
; #pragma unroll
;                 for (int ct = 0; ct < 4; ++ct)
; #pragma unroll
;                     for (int tt = 0; tt < 3; ++tt) acc[ct][tt] = __builtin_amdgcn_mfma_f32_16x16x32_bf16(fw[ct], fx[tt], acc[ct][tt], 0, 0, 0);
;             }
;             __syncthreads();
;         }
	ds_read_b128 v[102:105], v74 offset:49152
	ds_read_b128 v[106:109], v96 offset:32768
	ds_read_b128 v[110:113], v96 offset:36864
	ds_read_b128 v[114:117], v74 offset:53248
	v_mfma_f32_32x32x16_bf16 v[34:49], v[242:245], v[238:241], v[34:49]
	v_mfma_f32_32x32x16_bf16 v[18:33], v[246:249], v[238:241], v[18:33]
	v_lshl_add_u64 v[254:255], v[76:77], 0, s[22:23]
	global_load_lds_dwordx4 v[254:255], off
	v_lshl_add_u64 v[254:255], v[78:79], 0, s[22:23]
	s_mov_b32 m0, s7
	s_nop 0
	global_load_lds_dwordx4 v[254:255], off
	v_lshl_add_u64 v[254:255], v[80:81], 0, s[22:23]
	s_mov_b32 m0, s38
	v_mfma_f32_32x32x16_bf16 v[50:65], v[242:245], v[250:253], v[50:65]
	global_load_lds_dwordx4 v[254:255], off
	v_lshl_add_u64 v[254:255], v[82:83], 0, s[22:23]
	s_mov_b32 m0, s39
	s_nop 0
	global_load_lds_dwordx4 v[254:255], off
	v_lshl_add_u64 v[254:255], v[84:85], 0, s[22:23]
	s_mov_b32 m0, s50
	v_mfma_f32_32x32x16_bf16 v[2:17], v[246:249], v[250:253], v[2:17]
	global_load_lds_dwordx4 v[254:255], off
	v_lshl_add_u64 v[254:255], v[86:87], 0, s[22:23]
	s_mov_b32 m0, s51
	s_nop 0
	global_load_lds_dwordx4 v[254:255], off
	v_lshl_add_u64 v[254:255], v[88:89], 0, s[22:23]
	s_mov_b32 m0, s83
	s_nop 0
	global_load_lds_dwordx4 v[254:255], off
	v_lshl_add_u64 v[254:255], v[90:91], 0, s[22:23]
	s_mov_b32 m0, s90
	s_nop 0
	global_load_lds_dwordx4 v[254:255], off
	s_waitcnt lgkmcnt(0)
	ds_read_b128 v[238:241], v95 offset:49152
	ds_read_b128 v[242:245], v97 offset:32768
	ds_read_b128 v[246:249], v97 offset:36864
	ds_read_b128 v[250:253], v95 offset:53248
	v_mfma_f32_32x32x16_bf16 v[34:49], v[106:109], v[102:105], v[34:49]
	s_mov_b32 m0, s86
	v_mfma_f32_32x32x16_bf16 v[18:33], v[110:113], v[102:105], v[18:33]
	v_mfma_f32_32x32x16_bf16 v[50:65], v[106:109], v[114:117], v[50:65]
	v_mfma_f32_32x32x16_bf16 v[2:17], v[110:113], v[114:117], v[2:17]
	s_waitcnt lgkmcnt(0)
	ds_read_b128 v[102:105], v98 offset:49152
	ds_read_b128 v[106:109], v99 offset:32768
	ds_read_b128 v[110:113], v99 offset:36864
	ds_read_b128 v[114:117], v98 offset:53248
	v_mfma_f32_32x32x16_bf16 v[34:49], v[242:245], v[238:241], v[34:49]
	v_mfma_f32_32x32x16_bf16 v[18:33], v[246:249], v[238:241], v[18:33]
	v_mfma_f32_32x32x16_bf16 v[50:65], v[242:245], v[250:253], v[50:65]
	v_mfma_f32_32x32x16_bf16 v[2:17], v[246:249], v[250:253], v[2:17]
	s_waitcnt lgkmcnt(0)
	ds_read_b128 v[238:241], v100 offset:49152
	ds_read_b128 v[242:245], v101 offset:32768
	ds_read_b128 v[246:249], v101 offset:36864
	ds_read_b128 v[250:253], v100 offset:53248
	v_mfma_f32_32x32x16_bf16 v[34:49], v[106:109], v[102:105], v[34:49]
	v_mfma_f32_32x32x16_bf16 v[18:33], v[110:113], v[102:105], v[18:33]
	v_mfma_f32_32x32x16_bf16 v[50:65], v[106:109], v[114:117], v[50:65]
	v_mfma_f32_32x32x16_bf16 v[2:17], v[110:113], v[114:117], v[2:17]
	s_waitcnt vmcnt(0) lgkmcnt(0)
	s_barrier
	ds_read_b128 v[102:105], v74 offset:16384
	ds_read_b128 v[106:109], v96
	ds_read_b128 v[110:113], v96 offset:4096
	ds_read_b128 v[114:117], v74 offset:20480
	v_mfma_f32_32x32x16_bf16 v[34:49], v[242:245], v[238:241], v[34:49]
	v_mfma_f32_32x32x16_bf16 v[18:33], v[246:249], v[238:241], v[18:33]
	v_lshl_add_u64 v[254:255], v[76:77], 0, s[24:25]
	global_load_lds_dwordx4 v[254:255], off
	v_lshl_add_u64 v[254:255], v[78:79], 0, s[24:25]
	s_mov_b32 m0, s87
	s_nop 0
	global_load_lds_dwordx4 v[254:255], off
	v_lshl_add_u64 v[254:255], v[80:81], 0, s[24:25]
	s_mov_b32 m0, s88
	v_mfma_f32_32x32x16_bf16 v[50:65], v[242:245], v[250:253], v[50:65]
	global_load_lds_dwordx4 v[254:255], off
	v_lshl_add_u64 v[254:255], v[82:83], 0, s[24:25]
	s_mov_b32 m0, s89
	s_nop 0
	global_load_lds_dwordx4 v[254:255], off
	v_lshl_add_u64 v[254:255], v[84:85], 0, s[24:25]
	s_mov_b32 m0, s91
	v_mfma_f32_32x32x16_bf16 v[2:17], v[246:249], v[250:253], v[2:17]
	global_load_lds_dwordx4 v[254:255], off
	v_lshl_add_u64 v[254:255], v[86:87], 0, s[24:25]
	s_mov_b32 m0, s92
	s_nop 0
	global_load_lds_dwordx4 v[254:255], off
	v_lshl_add_u64 v[254:255], v[88:89], 0, s[24:25]
	s_mov_b32 m0, s93
	s_nop 0
	global_load_lds_dwordx4 v[254:255], off
	v_lshl_add_u64 v[254:255], v[90:91], 0, s[24:25]
	s_mov_b32 m0, s94
	s_nop 0
	global_load_lds_dwordx4 v[254:255], off
	s_waitcnt lgkmcnt(0)
	ds_read_b128 v[238:241], v95 offset:16384
	ds_read_b128 v[242:245], v97
	ds_read_b128 v[246:249], v97 offset:4096
	ds_read_b128 v[250:253], v95 offset:20480
	v_mfma_f32_32x32x16_bf16 v[34:49], v[106:109], v[102:105], v[34:49]
	s_mov_b32 m0, s1
	v_mfma_f32_32x32x16_bf16 v[18:33], v[110:113], v[102:105], v[18:33]
	v_mfma_f32_32x32x16_bf16 v[50:65], v[106:109], v[114:117], v[50:65]
	v_mfma_f32_32x32x16_bf16 v[2:17], v[110:113], v[114:117], v[2:17]
	s_waitcnt lgkmcnt(0)
	ds_read_b128 v[102:105], v98 offset:16384
	ds_read_b128 v[106:109], v99
	ds_read_b128 v[110:113], v99 offset:4096
	ds_read_b128 v[114:117], v98 offset:20480
	v_mfma_f32_32x32x16_bf16 v[34:49], v[242:245], v[238:241], v[34:49]
	v_mfma_f32_32x32x16_bf16 v[18:33], v[246:249], v[238:241], v[18:33]
	v_mfma_f32_32x32x16_bf16 v[50:65], v[242:245], v[250:253], v[50:65]
	v_mfma_f32_32x32x16_bf16 v[2:17], v[246:249], v[250:253], v[2:17]
	s_waitcnt lgkmcnt(0)
	ds_read_b128 v[238:241], v100 offset:16384
	ds_read_b128 v[242:245], v101
	ds_read_b128 v[246:249], v101 offset:4096
	ds_read_b128 v[250:253], v100 offset:20480
	v_mfma_f32_32x32x16_bf16 v[34:49], v[106:109], v[102:105], v[34:49]
	v_mfma_f32_32x32x16_bf16 v[18:33], v[110:113], v[102:105], v[18:33]
	v_mfma_f32_32x32x16_bf16 v[50:65], v[106:109], v[114:117], v[50:65]
	v_mfma_f32_32x32x16_bf16 v[2:17], v[110:113], v[114:117], v[2:17]
	s_waitcnt vmcnt(0) lgkmcnt(0)
	s_barrier
; DI void gemm_out(const Params& p, char* lds) {
;     ...
;         for (int kt = 0; kt < 16; ++kt) {
;             if (kt + 1 < 16) OSTAGE((kt + 1) & 1, kt + 1);
;             const char* sb = lds + (kt & 1) * 28672; const char* sa = sb + 16384;
; #pragma unroll
;             for (int ks = 0; ks < 2; ++ks) {
;                 bf16x8 fw[4], fx[3];
; #pragma unroll
;                 for (int ct = 0; ct < 4; ++ct) fw[ct] = *(const bf16x8*)(sb + swz(wn * 64 + ct * 16 + q, 4 * ks + g));
; #pragma unroll
;                 for (int tt = 0; tt < 3; ++tt) fx[tt] = *(const bf16x8*)(sa + swz(wm * 48 + tt * 16 + q, 4 * ks + g));
; #pragma unroll
;                 for (int ct = 0; ct < 4; ++ct)
; #pragma unroll
;                     for (int tt = 0; tt < 3; ++tt) acc[ct][tt] = __builtin_amdgcn_mfma_f32_16x16x32_bf16(fw[ct], fx[tt], acc[ct][tt], 0, 0, 0);
;             }
;             __syncthreads();
;         }
	ds_read_b128 v[102:105], v74 offset:49152
	ds_read_b128 v[106:109], v96 offset:32768
	ds_read_b128 v[110:113], v96 offset:36864
	ds_read_b128 v[114:117], v74 offset:53248
	v_mfma_f32_32x32x16_bf16 v[34:49], v[242:245], v[238:241], v[34:49]
	v_mfma_f32_32x32x16_bf16 v[18:33], v[246:249], v[238:241], v[18:33]
	v_lshl_add_u64 v[254:255], v[76:77], 0, s[26:27]
	global_load_lds_dwordx4 v[254:255], off
	v_lshl_add_u64 v[254:255], v[78:79], 0, s[26:27]
	s_mov_b32 m0, s7
	s_nop 0
	global_load_lds_dwordx4 v[254:255], off
	v_lshl_add_u64 v[254:255], v[80:81], 0, s[26:27]
	s_mov_b32 m0, s38
	v_mfma_f32_32x32x16_bf16 v[50:65], v[242:245], v[250:253], v[50:65]
	global_load_lds_dwordx4 v[254:255], off
	v_lshl_add_u64 v[254:255], v[82:83], 0, s[26:27]
	s_mov_b32 m0, s39
	s_nop 0
	global_load_lds_dwordx4 v[254:255], off
	v_lshl_add_u64 v[254:255], v[84:85], 0, s[26:27]
	s_mov_b32 m0, s50
	v_mfma_f32_32x32x16_bf16 v[2:17], v[246:249], v[250:253], v[2:17]
	global_load_lds_dwordx4 v[254:255], off
	v_lshl_add_u64 v[254:255], v[86:87], 0, s[26:27]
	s_mov_b32 m0, s51
	s_nop 0
	global_load_lds_dwordx4 v[254:255], off
	v_lshl_add_u64 v[254:255], v[88:89], 0, s[26:27]
	s_mov_b32 m0, s83
	s_nop 0
	global_load_lds_dwordx4 v[254:255], off
	v_lshl_add_u64 v[254:255], v[90:91], 0, s[26:27]
	s_mov_b32 m0, s90
	s_nop 0
	global_load_lds_dwordx4 v[254:255], off
	s_waitcnt lgkmcnt(0)
	ds_read_b128 v[238:241], v95 offset:49152
	ds_read_b128 v[242:245], v97 offset:32768
	ds_read_b128 v[246:249], v97 offset:36864
	ds_read_b128 v[250:253], v95 offset:53248
	v_mfma_f32_32x32x16_bf16 v[34:49], v[106:109], v[102:105], v[34:49]
	s_mov_b32 m0, s86
	v_mfma_f32_32x32x16_bf16 v[18:33], v[110:113], v[102:105], v[18:33]
	v_mfma_f32_32x32x16_bf16 v[50:65], v[106:109], v[114:117], v[50:65]
	v_mfma_f32_32x32x16_bf16 v[2:17], v[110:113], v[114:117], v[2:17]
	s_waitcnt lgkmcnt(0)
	ds_read_b128 v[102:105], v98 offset:49152
	ds_read_b128 v[106:109], v99 offset:32768
	ds_read_b128 v[110:113], v99 offset:36864
	ds_read_b128 v[114:117], v98 offset:53248
	v_mfma_f32_32x32x16_bf16 v[34:49], v[242:245], v[238:241], v[34:49]
	v_mfma_f32_32x32x16_bf16 v[18:33], v[246:249], v[238:241], v[18:33]
	v_mfma_f32_32x32x16_bf16 v[50:65], v[242:245], v[250:253], v[50:65]
	v_mfma_f32_32x32x16_bf16 v[2:17], v[246:249], v[250:253], v[2:17]
	s_waitcnt lgkmcnt(0)
	ds_read_b128 v[238:241], v100 offset:49152
	ds_read_b128 v[242:245], v101 offset:32768
	ds_read_b128 v[246:249], v101 offset:36864
	ds_read_b128 v[250:253], v100 offset:53248
	v_mfma_f32_32x32x16_bf16 v[34:49], v[106:109], v[102:105], v[34:49]
	v_mfma_f32_32x32x16_bf16 v[18:33], v[110:113], v[102:105], v[18:33]
	v_mfma_f32_32x32x16_bf16 v[50:65], v[106:109], v[114:117], v[50:65]
	v_mfma_f32_32x32x16_bf16 v[2:17], v[110:113], v[114:117], v[2:17]
	s_waitcnt vmcnt(0) lgkmcnt(0)
	s_barrier
	ds_read_b128 v[102:105], v74 offset:16384
	ds_read_b128 v[106:109], v96
	ds_read_b128 v[110:113], v96 offset:4096
	ds_read_b128 v[114:117], v74 offset:20480
	v_mfma_f32_32x32x16_bf16 v[34:49], v[242:245], v[238:241], v[34:49]
	v_mfma_f32_32x32x16_bf16 v[18:33], v[246:249], v[238:241], v[18:33]
	v_lshl_add_u64 v[254:255], v[76:77], 0, s[28:29]
	global_load_lds_dwordx4 v[254:255], off
	v_lshl_add_u64 v[254:255], v[78:79], 0, s[28:29]
	s_mov_b32 m0, s87
	s_nop 0
	global_load_lds_dwordx4 v[254:255], off
	v_lshl_add_u64 v[254:255], v[80:81], 0, s[28:29]
	s_mov_b32 m0, s88
	v_mfma_f32_32x32x16_bf16 v[50:65], v[242:245], v[250:253], v[50:65]
	global_load_lds_dwordx4 v[254:255], off
	v_lshl_add_u64 v[254:255], v[82:83], 0, s[28:29]
	s_mov_b32 m0, s89
	s_nop 0
	global_load_lds_dwordx4 v[254:255], off
	v_lshl_add_u64 v[254:255], v[84:85], 0, s[28:29]
	s_mov_b32 m0, s91
	v_mfma_f32_32x32x16_bf16 v[2:17], v[246:249], v[250:253], v[2:17]
	global_load_lds_dwordx4 v[254:255], off
	v_lshl_add_u64 v[254:255], v[86:87], 0, s[28:29]
	s_mov_b32 m0, s92
	s_nop 0
	global_load_lds_dwordx4 v[254:255], off
	v_lshl_add_u64 v[254:255], v[88:89], 0, s[28:29]
	s_mov_b32 m0, s93
	s_nop 0
	global_load_lds_dwordx4 v[254:255], off
	v_lshl_add_u64 v[254:255], v[90:91], 0, s[28:29]
	s_mov_b32 m0, s94
	s_nop 0
	global_load_lds_dwordx4 v[254:255], off
	s_waitcnt lgkmcnt(0)
	ds_read_b128 v[238:241], v95 offset:16384
	ds_read_b128 v[242:245], v97
	ds_read_b128 v[246:249], v97 offset:4096
	ds_read_b128 v[250:253], v95 offset:20480
	v_mfma_f32_32x32x16_bf16 v[34:49], v[106:109], v[102:105], v[34:49]
	s_mov_b32 m0, s1
	v_mfma_f32_32x32x16_bf16 v[18:33], v[110:113], v[102:105], v[18:33]
	v_mfma_f32_32x32x16_bf16 v[50:65], v[106:109], v[114:117], v[50:65]
	v_mfma_f32_32x32x16_bf16 v[2:17], v[110:113], v[114:117], v[2:17]
	s_waitcnt lgkmcnt(0)
	ds_read_b128 v[102:105], v98 offset:16384
	ds_read_b128 v[106:109], v99
	ds_read_b128 v[110:113], v99 offset:4096
	ds_read_b128 v[114:117], v98 offset:20480
	v_mfma_f32_32x32x16_bf16 v[34:49], v[242:245], v[238:241], v[34:49]
	v_mfma_f32_32x32x16_bf16 v[18:33], v[246:249], v[238:241], v[18:33]
	v_mfma_f32_32x32x16_bf16 v[50:65], v[242:245], v[250:253], v[50:65]
	v_mfma_f32_32x32x16_bf16 v[2:17], v[246:249], v[250:253], v[2:17]
	s_waitcnt lgkmcnt(0)
	ds_read_b128 v[238:241], v100 offset:16384
	ds_read_b128 v[242:245], v101
	ds_read_b128 v[246:249], v101 offset:4096
	ds_read_b128 v[250:253], v100 offset:20480
	v_mfma_f32_32x32x16_bf16 v[34:49], v[106:109], v[102:105], v[34:49]
	v_mfma_f32_32x32x16_bf16 v[18:33], v[110:113], v[102:105], v[18:33]
	v_mfma_f32_32x32x16_bf16 v[50:65], v[106:109], v[114:117], v[50:65]
	v_mfma_f32_32x32x16_bf16 v[2:17], v[110:113], v[114:117], v[2:17]
	s_waitcnt vmcnt(0) lgkmcnt(0)
	s_barrier
; DI void gemm_out(const Params& p, char* lds) {
;     ...
;         for (int kt = 0; kt < 16; ++kt) {
;             if (kt + 1 < 16) OSTAGE((kt + 1) & 1, kt + 1);
;             const char* sb = lds + (kt & 1) * 28672; const char* sa = sb + 16384;
; #pragma unroll
;             for (int ks = 0; ks < 2; ++ks) {
;                 bf16x8 fw[4], fx[3];
; #pragma unroll
;                 for (int ct = 0; ct < 4; ++ct) fw[ct] = *(const bf16x8*)(sb + swz(wn * 64 + ct * 16 + q, 4 * ks + g));
; #pragma unroll
;                 for (int tt = 0; tt < 3; ++tt) fx[tt] = *(const bf16x8*)(sa + swz(wm * 48 + tt * 16 + q, 4 * ks + g));
; #pragma unroll
;                 for (int ct = 0; ct < 4; ++ct)
; #pragma unroll
;                     for (int tt = 0; tt < 3; ++tt) acc[ct][tt] = __builtin_amdgcn_mfma_f32_16x16x32_bf16(fw[ct], fx[tt], acc[ct][tt], 0, 0, 0);
;             }
;             __syncthreads();
;         }
	ds_read_b128 v[102:105], v74 offset:49152
	ds_read_b128 v[106:109], v96 offset:32768
	ds_read_b128 v[110:113], v96 offset:36864
	ds_read_b128 v[114:117], v74 offset:53248
	v_mfma_f32_32x32x16_bf16 v[34:49], v[242:245], v[238:241], v[34:49]
	v_mfma_f32_32x32x16_bf16 v[18:33], v[246:249], v[238:241], v[18:33]
	v_lshl_add_u64 v[254:255], v[76:77], 0, s[30:31]
	global_load_lds_dwordx4 v[254:255], off
	v_lshl_add_u64 v[254:255], v[78:79], 0, s[30:31]
	s_mov_b32 m0, s7
	s_nop 0
	global_load_lds_dwordx4 v[254:255], off
	v_lshl_add_u64 v[254:255], v[80:81], 0, s[30:31]
	s_mov_b32 m0, s38
	v_mfma_f32_32x32x16_bf16 v[50:65], v[242:245], v[250:253], v[50:65]
	global_load_lds_dwordx4 v[254:255], off
	v_lshl_add_u64 v[254:255], v[82:83], 0, s[30:31]
	s_mov_b32 m0, s39
	s_nop 0
	global_load_lds_dwordx4 v[254:255], off
	v_lshl_add_u64 v[254:255], v[84:85], 0, s[30:31]
	s_mov_b32 m0, s50
	v_mfma_f32_32x32x16_bf16 v[2:17], v[246:249], v[250:253], v[2:17]
	global_load_lds_dwordx4 v[254:255], off
	v_lshl_add_u64 v[254:255], v[86:87], 0, s[30:31]
	s_mov_b32 m0, s51
	s_nop 0
	global_load_lds_dwordx4 v[254:255], off
	v_lshl_add_u64 v[254:255], v[88:89], 0, s[30:31]
	s_mov_b32 m0, s83
	s_nop 0
	global_load_lds_dwordx4 v[254:255], off
	v_lshl_add_u64 v[254:255], v[90:91], 0, s[30:31]
	s_mov_b32 m0, s90
	s_nop 0
	global_load_lds_dwordx4 v[254:255], off
	s_waitcnt lgkmcnt(0)
	ds_read_b128 v[238:241], v95 offset:49152
	ds_read_b128 v[242:245], v97 offset:32768
	ds_read_b128 v[246:249], v97 offset:36864
	ds_read_b128 v[250:253], v95 offset:53248
	v_mfma_f32_32x32x16_bf16 v[34:49], v[106:109], v[102:105], v[34:49]
	s_mov_b32 m0, s86
	v_mfma_f32_32x32x16_bf16 v[18:33], v[110:113], v[102:105], v[18:33]
	v_mfma_f32_32x32x16_bf16 v[50:65], v[106:109], v[114:117], v[50:65]
	v_mfma_f32_32x32x16_bf16 v[2:17], v[110:113], v[114:117], v[2:17]
	s_waitcnt lgkmcnt(0)
	ds_read_b128 v[102:105], v98 offset:49152
	ds_read_b128 v[106:109], v99 offset:32768
	ds_read_b128 v[110:113], v99 offset:36864
	ds_read_b128 v[114:117], v98 offset:53248
	v_mfma_f32_32x32x16_bf16 v[34:49], v[242:245], v[238:241], v[34:49]
	v_mfma_f32_32x32x16_bf16 v[18:33], v[246:249], v[238:241], v[18:33]
	v_mfma_f32_32x32x16_bf16 v[50:65], v[242:245], v[250:253], v[50:65]
	v_mfma_f32_32x32x16_bf16 v[2:17], v[246:249], v[250:253], v[2:17]
	s_waitcnt lgkmcnt(0)
	ds_read_b128 v[238:241], v100 offset:49152
	ds_read_b128 v[242:245], v101 offset:32768
	ds_read_b128 v[246:249], v101 offset:36864
	ds_read_b128 v[250:253], v100 offset:53248
	v_mfma_f32_32x32x16_bf16 v[34:49], v[106:109], v[102:105], v[34:49]
	v_mfma_f32_32x32x16_bf16 v[18:33], v[110:113], v[102:105], v[18:33]
	v_mfma_f32_32x32x16_bf16 v[50:65], v[106:109], v[114:117], v[50:65]
	v_mfma_f32_32x32x16_bf16 v[2:17], v[110:113], v[114:117], v[2:17]
	s_waitcnt vmcnt(0) lgkmcnt(0)
	s_barrier
	ds_read_b128 v[102:105], v74 offset:16384
	ds_read_b128 v[106:109], v96
	ds_read_b128 v[110:113], v96 offset:4096
	ds_read_b128 v[114:117], v74 offset:20480
	v_mfma_f32_32x32x16_bf16 v[34:49], v[242:245], v[238:241], v[34:49]
	v_mfma_f32_32x32x16_bf16 v[18:33], v[246:249], v[238:241], v[18:33]
	v_lshl_add_u64 v[254:255], v[76:77], 0, s[36:37]
	global_load_lds_dwordx4 v[254:255], off
	v_lshl_add_u64 v[254:255], v[78:79], 0, s[36:37]
	s_mov_b32 m0, s87
	s_nop 0
	global_load_lds_dwordx4 v[254:255], off
	v_lshl_add_u64 v[254:255], v[80:81], 0, s[36:37]
	s_mov_b32 m0, s88
	v_mfma_f32_32x32x16_bf16 v[50:65], v[242:245], v[250:253], v[50:65]
	global_load_lds_dwordx4 v[254:255], off
	v_lshl_add_u64 v[254:255], v[82:83], 0, s[36:37]
	s_mov_b32 m0, s89
	s_nop 0
	global_load_lds_dwordx4 v[254:255], off
	v_lshl_add_u64 v[254:255], v[84:85], 0, s[36:37]
	s_mov_b32 m0, s91
	v_mfma_f32_32x32x16_bf16 v[2:17], v[246:249], v[250:253], v[2:17]
	global_load_lds_dwordx4 v[254:255], off
	v_lshl_add_u64 v[254:255], v[86:87], 0, s[36:37]
	s_mov_b32 m0, s92
	s_nop 0
	global_load_lds_dwordx4 v[254:255], off
	v_lshl_add_u64 v[254:255], v[88:89], 0, s[36:37]
	s_mov_b32 m0, s93
	s_nop 0
	global_load_lds_dwordx4 v[254:255], off
	v_lshl_add_u64 v[254:255], v[90:91], 0, s[36:37]
	s_mov_b32 m0, s94
	s_nop 0
	global_load_lds_dwordx4 v[254:255], off
	s_waitcnt lgkmcnt(0)
	ds_read_b128 v[238:241], v95 offset:16384
	ds_read_b128 v[242:245], v97
	ds_read_b128 v[246:249], v97 offset:4096
	ds_read_b128 v[250:253], v95 offset:20480
	v_mfma_f32_32x32x16_bf16 v[34:49], v[106:109], v[102:105], v[34:49]
	s_mov_b32 m0, s1
	v_mfma_f32_32x32x16_bf16 v[18:33], v[110:113], v[102:105], v[18:33]
	v_mfma_f32_32x32x16_bf16 v[50:65], v[106:109], v[114:117], v[50:65]
	v_mfma_f32_32x32x16_bf16 v[2:17], v[110:113], v[114:117], v[2:17]
	s_waitcnt lgkmcnt(0)
	ds_read_b128 v[102:105], v98 offset:16384
	ds_read_b128 v[106:109], v99
	ds_read_b128 v[110:113], v99 offset:4096
	ds_read_b128 v[114:117], v98 offset:20480
	v_mfma_f32_32x32x16_bf16 v[34:49], v[242:245], v[238:241], v[34:49]
	v_mfma_f32_32x32x16_bf16 v[18:33], v[246:249], v[238:241], v[18:33]
	v_mfma_f32_32x32x16_bf16 v[50:65], v[242:245], v[250:253], v[50:65]
	v_mfma_f32_32x32x16_bf16 v[2:17], v[246:249], v[250:253], v[2:17]
	s_waitcnt lgkmcnt(0)
	ds_read_b128 v[238:241], v100 offset:16384
	ds_read_b128 v[242:245], v101
	ds_read_b128 v[246:249], v101 offset:4096
	ds_read_b128 v[250:253], v100 offset:20480
	v_mfma_f32_32x32x16_bf16 v[34:49], v[106:109], v[102:105], v[34:49]
	v_mfma_f32_32x32x16_bf16 v[18:33], v[110:113], v[102:105], v[18:33]
	v_mfma_f32_32x32x16_bf16 v[50:65], v[106:109], v[114:117], v[50:65]
	v_mfma_f32_32x32x16_bf16 v[2:17], v[110:113], v[114:117], v[2:17]
	s_waitcnt vmcnt(0) lgkmcnt(0)
	s_barrier
; #define TILE_MN(t, M0, N0) do { int pan_ = (t) / (mtiles * 8); if (pan_ >= npan) pan_ = npan - 1; const int pw_ = (pan_ == npan - 1) ? ntiles - 8 * pan_ : 8; const int loc_ = (t) - pan_ * mtiles * 8; \
;         M0 = (loc_ / pw_) * 128; N0 = (8 * pan_ + loc_ % pw_) * 128; } while (0)
; template <class Epi>
; DI void gemm_phase(const u16* __restrict__ A, const u16* __restrict__ B, int mtiles, int ntiles, char* lds, const Epi& epi) {
;     ...
;         const int nxt = tile + (int)gridDim.x; int m1 = 0, n1 = 0;
;         if (nxt < ntile) { TILE_MN(nxt, m1, n1); GSTAGE(0, 0, A + (size_t)m1 * 1024, B + (size_t)n1 * 1024); }
; DI void gemm_out(const Params& p, char* lds) {
;     ...
;         for (int kt = 0; kt < 16; ++kt) {
;             if (kt + 1 < 16) OSTAGE((kt + 1) & 1, kt + 1);
;             const char* sb = lds + (kt & 1) * 28672; const char* sa = sb + 16384;
; #pragma unroll
;             for (int ks = 0; ks < 2; ++ks) {
;                 bf16x8 fw[4], fx[3];
; #pragma unroll
;                 for (int ct = 0; ct < 4; ++ct) fw[ct] = *(const bf16x8*)(sb + swz(wn * 64 + ct * 16 + q, 4 * ks + g));
; #pragma unroll
;                 for (int tt = 0; tt < 3; ++tt) fx[tt] = *(const bf16x8*)(sa + swz(wm * 48 + tt * 16 + q, 4 * ks + g));
; #pragma unroll
;                 for (int ct = 0; ct < 4; ++ct)
; #pragma unroll
;                     for (int tt = 0; tt < 3; ++tt) acc[ct][tt] = __builtin_amdgcn_mfma_f32_16x16x32_bf16(fw[ct], fx[tt], acc[ct][tt], 0, 0, 0);
;             }
;             __syncthreads();
;         }
	ds_read_b128 v[102:105], v74 offset:49152
	ds_read_b128 v[106:109], v96 offset:32768
	ds_read_b128 v[110:113], v96 offset:36864
	ds_read_b128 v[114:117], v74 offset:53248
	v_mfma_f32_32x32x16_bf16 v[34:49], v[242:245], v[238:241], v[34:49]
	v_mfma_f32_32x32x16_bf16 v[18:33], v[246:249], v[238:241], v[18:33]
	v_lshl_add_u64 v[254:255], v[76:77], 0, s[68:69]
	global_load_lds_dwordx4 v[254:255], off
	v_lshl_add_u64 v[254:255], v[78:79], 0, s[68:69]
	s_mov_b32 m0, s7
	v_lshl_add_u64 v[76:77], v[76:77], 0, s[70:71]
	global_load_lds_dwordx4 v[254:255], off
	v_lshl_add_u64 v[254:255], v[80:81], 0, s[68:69]
	s_mov_b32 m0, s38
	v_mfma_f32_32x32x16_bf16 v[50:65], v[242:245], v[250:253], v[50:65]
	global_load_lds_dwordx4 v[254:255], off
	v_lshl_add_u64 v[254:255], v[82:83], 0, s[68:69]
	s_mov_b32 m0, s39
	s_nop 0
	global_load_lds_dwordx4 v[254:255], off
	v_lshl_add_u64 v[254:255], v[84:85], 0, s[68:69]
	s_mov_b32 m0, s50
	v_mfma_f32_32x32x16_bf16 v[2:17], v[246:249], v[250:253], v[2:17]
	global_load_lds_dwordx4 v[254:255], off
	v_lshl_add_u64 v[254:255], v[86:87], 0, s[68:69]
	s_mov_b32 m0, s51
	s_nop 0
	global_load_lds_dwordx4 v[254:255], off
	v_lshl_add_u64 v[254:255], v[88:89], 0, s[68:69]
	s_mov_b32 m0, s83
	s_nop 0
	global_load_lds_dwordx4 v[254:255], off
	v_lshl_add_u64 v[254:255], v[90:91], 0, s[68:69]
	s_mov_b32 m0, s90
	s_nop 0
	global_load_lds_dwordx4 v[254:255], off
	s_waitcnt lgkmcnt(0)
	ds_read_b128 v[238:241], v95 offset:49152
	ds_read_b128 v[242:245], v97 offset:32768
	ds_read_b128 v[246:249], v97 offset:36864
	ds_read_b128 v[250:253], v95 offset:53248
	v_mfma_f32_32x32x16_bf16 v[34:49], v[106:109], v[102:105], v[34:49]
	s_mov_b32 m0, s86
	s_mov_b32 s86, 0
	v_mfma_f32_32x32x16_bf16 v[18:33], v[110:113], v[102:105], v[18:33]
	v_mfma_f32_32x32x16_bf16 v[50:65], v[106:109], v[114:117], v[50:65]
	v_mfma_f32_32x32x16_bf16 v[2:17], v[110:113], v[114:117], v[2:17]
	s_waitcnt lgkmcnt(0)
	ds_read_b128 v[102:105], v98 offset:49152
	ds_read_b128 v[106:109], v99 offset:32768
	ds_read_b128 v[110:113], v99 offset:36864
	ds_read_b128 v[114:117], v98 offset:53248
	v_mfma_f32_32x32x16_bf16 v[34:49], v[242:245], v[238:241], v[34:49]
	v_mfma_f32_32x32x16_bf16 v[18:33], v[246:249], v[238:241], v[18:33]
	v_mfma_f32_32x32x16_bf16 v[50:65], v[242:245], v[250:253], v[50:65]
	v_mfma_f32_32x32x16_bf16 v[2:17], v[246:249], v[250:253], v[2:17]
	s_waitcnt lgkmcnt(0)
	ds_read_b128 v[238:241], v100 offset:49152
	ds_read_b128 v[242:245], v101 offset:32768
	ds_read_b128 v[246:249], v101 offset:36864
	ds_read_b128 v[250:253], v100 offset:53248
	v_mfma_f32_32x32x16_bf16 v[34:49], v[106:109], v[102:105], v[34:49]
	v_mfma_f32_32x32x16_bf16 v[18:33], v[110:113], v[102:105], v[18:33]
	v_mfma_f32_32x32x16_bf16 v[50:65], v[106:109], v[114:117], v[50:65]
	v_mfma_f32_32x32x16_bf16 v[2:17], v[110:113], v[114:117], v[2:17]
	s_waitcnt vmcnt(0) lgkmcnt(0)
	s_barrier
	global_load_lds_dwordx4 v[76:77], off
	v_lshl_add_u64 v[76:77], v[78:79], 0, s[70:71]
	s_mov_b32 m0, s87
	v_mfma_f32_32x32x16_bf16 v[34:49], v[242:245], v[238:241], v[34:49]
	global_load_lds_dwordx4 v[76:77], off
	v_lshl_add_u64 v[76:77], v[80:81], 0, s[70:71]
	s_mov_b32 m0, s88
	s_mov_b32 s88, 0
	global_load_lds_dwordx4 v[76:77], off
	v_lshl_add_u64 v[76:77], v[82:83], 0, s[70:71]
	s_mov_b32 m0, s89
	v_mfma_f32_32x32x16_bf16 v[18:33], v[246:249], v[238:241], v[18:33]
	global_load_lds_dwordx4 v[76:77], off
	v_lshl_add_u64 v[76:77], v[84:85], 0, s[70:71]
	s_mov_b32 m0, s91
	s_nop 0
	global_load_lds_dwordx4 v[76:77], off
	v_lshl_add_u64 v[76:77], v[86:87], 0, s[70:71]
	s_mov_b32 m0, s92
	v_mfma_f32_32x32x16_bf16 v[50:65], v[242:245], v[250:253], v[50:65]
	global_load_lds_dwordx4 v[76:77], off
	v_lshl_add_u64 v[76:77], v[88:89], 0, s[70:71]
	s_mov_b32 m0, s93
	s_nop 0
	global_load_lds_dwordx4 v[76:77], off
	v_lshl_add_u64 v[76:77], v[90:91], 0, s[70:71]
	s_mov_b32 m0, s94
	v_mfma_f32_32x32x16_bf16 v[2:17], v[246:249], v[250:253], v[2:17]
	global_load_lds_dwordx4 v[76:77], off
	ds_read_b128 v[76:79], v74 offset:16384
	ds_read_b128 v[80:83], v96
	ds_read_b128 v[84:87], v96 offset:4096
	ds_read_b128 v[88:91], v74 offset:20480
	s_waitcnt lgkmcnt(0)
	v_mfma_f32_32x32x16_bf16 v[34:49], v[80:83], v[76:79], v[34:49]
	v_mfma_f32_32x32x16_bf16 v[18:33], v[84:87], v[76:79], v[18:33]
	v_mfma_f32_32x32x16_bf16 v[50:65], v[80:83], v[88:91], v[50:65]
	v_mfma_f32_32x32x16_bf16 v[2:17], v[84:87], v[88:91], v[2:17]
	ds_read_b128 v[76:79], v95 offset:16384
	ds_read_b128 v[80:83], v97
	ds_read_b128 v[84:87], v97 offset:4096
	ds_read_b128 v[88:91], v95 offset:20480
	s_waitcnt lgkmcnt(0)
	v_mfma_f32_32x32x16_bf16 v[34:49], v[80:83], v[76:79], v[34:49]
	v_mfma_f32_32x32x16_bf16 v[18:33], v[84:87], v[76:79], v[18:33]
	v_mfma_f32_32x32x16_bf16 v[50:65], v[80:83], v[88:91], v[50:65]
	v_mfma_f32_32x32x16_bf16 v[2:17], v[84:87], v[88:91], v[2:17]
	ds_read_b128 v[76:79], v98 offset:16384
	ds_read_b128 v[80:83], v99
	ds_read_b128 v[84:87], v99 offset:4096
	ds_read_b128 v[88:91], v98 offset:20480
	s_waitcnt lgkmcnt(0)
	v_mfma_f32_32x32x16_bf16 v[34:49], v[80:83], v[76:79], v[34:49]
	v_mfma_f32_32x32x16_bf16 v[18:33], v[84:87], v[76:79], v[18:33]
	v_mfma_f32_32x32x16_bf16 v[50:65], v[80:83], v[88:91], v[50:65]
	v_mfma_f32_32x32x16_bf16 v[2:17], v[84:87], v[88:91], v[2:17]
	ds_read_b128 v[76:79], v100 offset:16384
	ds_read_b128 v[80:83], v101
	ds_read_b128 v[84:87], v101 offset:4096
	ds_read_b128 v[88:91], v100 offset:20480
	s_waitcnt vmcnt(0) lgkmcnt(0)
	s_barrier
	s_cbranch_scc1 .Lo_skipnext
	s_mov_b32 m0, s1
	s_lshr_b32 s86, s33, 3
	s_lshl_b32 s86, s86, 7
	s_and_b32 s88, s33, 7
	s_lshl_b32 s88, s88, 7
	s_ashr_i32 s87, s86, 31
	s_lshl_b64 s[92:93], s[86:87], 11
	s_add_u32 s92, s54, s92
	s_addc_u32 s93, s55, s93
	s_ashr_i32 s89, s88, 31
	s_lshl_b64 s[94:95], s[88:89], 11
	v_readlane_b32 s1, v236, 9
	s_add_u32 s94, s1, s94
	v_readlane_b32 s1, v236, 11
	s_addc_u32 s95, s1, s95
	v_lshl_add_u64 v[118:119], s[92:93], 0, v[66:67]
	global_load_lds_dwordx4 v[118:119], off
	v_lshl_add_u64 v[66:67], s[94:95], 0, v[66:67]
	s_mov_b32 m0, s7
	s_nop 0
	global_load_lds_dwordx4 v[66:67], off
	v_lshl_add_u64 v[66:67], s[92:93], 0, v[68:69]
	s_mov_b32 m0, s38
	s_nop 0
	global_load_lds_dwordx4 v[66:67], off
	v_lshl_add_u64 v[66:67], s[94:95], 0, v[68:69]
	s_mov_b32 m0, s39
	s_nop 0
	global_load_lds_dwordx4 v[66:67], off
	v_lshl_add_u64 v[66:67], s[92:93], 0, v[70:71]
	s_mov_b32 m0, s50
	s_nop 0
	global_load_lds_dwordx4 v[66:67], off
	v_lshl_add_u64 v[66:67], s[94:95], 0, v[70:71]
	s_mov_b32 m0, s51
	s_nop 0
	global_load_lds_dwordx4 v[66:67], off
	v_lshl_add_u64 v[66:67], s[92:93], 0, v[72:73]
	s_mov_b32 m0, s83
	s_nop 0
	global_load_lds_dwordx4 v[66:67], off
	v_lshl_add_u64 v[66:67], s[94:95], 0, v[72:73]
	s_mov_b32 m0, s90
	s_nop 0
	global_load_lds_dwordx4 v[66:67], off
; DI void gemm_out(const Params& p, char* lds) {
;     ...
;             for (int ks = 0; ks < 2; ++ks) {
;                 bf16x8 fw[4], fx[3];
; #pragma unroll
;                 for (int ct = 0; ct < 4; ++ct) fw[ct] = *(const bf16x8*)(sb + swz(wn * 64 + ct * 16 + q, 4 * ks + g));
; #pragma unroll
;                 for (int tt = 0; tt < 3; ++tt) fx[tt] = *(const bf16x8*)(sa + swz(wm * 48 + tt * 16 + q, 4 * ks + g));
; #pragma unroll
;                 for (int ct = 0; ct < 4; ++ct)
; #pragma unroll
;                     for (int tt = 0; tt < 3; ++tt) acc[ct][tt] = __builtin_amdgcn_mfma_f32_16x16x32_bf16(fw[ct], fx[tt], acc[ct][tt], 0, 0, 0);
;             }
;             __syncthreads();
;         }
;     ...
; #pragma unroll
;         for (int tt = 0; tt < 3; ++tt) {
;             const int row = m0 + wm * 48 + tt * 16 + q;
;             const float* xr = row < NTP ? p.x_p + (size_t)row * DM : p.x_s + (size_t)(row - NTP) * DM;
;             float* o = p.out + (size_t)row * DM;
; #pragma unroll
;             for (int ct = 0; ct < 4; ++ct) { const int col = n0 + wn * 64 + ct * 16 + 4 * g; const float4 xv = xres[tt][ct];
;                 const f32x4 w = {xv.x + acc[ct][tt][0], xv.y + acc[ct][tt][1], xv.z + acc[ct][tt][2], xv.w + acc[ct][tt][3]}; __builtin_nontemporal_store(w, (f32x4*)(o + col)); }
.Lo_skipnext:
	v_readfirstlane_b32 s96, v0
	s_lshr_b32 s96, s96, 6
	s_lshr_b32 s98, s96, 1
	s_and_b32 s96, s96, 1
	s_lshl_b32 s97, s96, 6
	s_add_i32 s97, s97, s82
	s_cmp_lt_u32 s82, 0x4000
	s_cselect_b32 s2, s56, s58
	s_cselect_b32 s3, s57, s59
	s_cselect_b32 s99, 0, 0x4000
	s_sub_i32 s99, s97, s99
	s_lshl_b32 s98, s98, 6
	s_add_i32 s98, s98, s0
	v_and_b32_e32 v184, 31, v0
	v_bfe_u32 v185, v0, 5, 1
	v_lshlrev_b32_e32 v185, 14, v185
	v_add_u32_e32 v186, s98, v184
	v_lshl_add_u32 v186, v186, 2, v185
	s_lshl_b32 s97, s97, 12
	s_lshl_b32 s99, s99, 12
	v_add_u32_e32 v188, s97, v186
	v_add_u32_e32 v187, s99, v186
	v_mfma_f32_32x32x16_bf16 v[34:49], v[80:83], v[76:79], v[34:49]
	global_load_dword v120, v187, s[2:3] nt
	global_load_dword v121, v187, s[2:3] offset:128 nt
	v_add_u32_e32 v187, 0x1000, v187
	global_load_dword v122, v187, s[2:3] nt
	global_load_dword v123, v187, s[2:3] offset:128 nt
	v_add_u32_e32 v187, 0x1000, v187
	v_mfma_f32_32x32x16_bf16 v[18:33], v[84:87], v[76:79], v[18:33]
	global_load_dword v124, v187, s[2:3] nt
	global_load_dword v125, v187, s[2:3] offset:128 nt
	v_add_u32_e32 v187, 0x1000, v187
	global_load_dword v126, v187, s[2:3] nt
	global_load_dword v127, v187, s[2:3] offset:128 nt
	v_add_u32_e32 v187, 0x5000, v187
	v_mfma_f32_32x32x16_bf16 v[50:65], v[80:83], v[88:91], v[50:65]
	global_load_dword v128, v187, s[2:3] nt
	global_load_dword v129, v187, s[2:3] offset:128 nt
	v_add_u32_e32 v187, 0x1000, v187
	global_load_dword v130, v187, s[2:3] nt
	global_load_dword v131, v187, s[2:3] offset:128 nt
	v_add_u32_e32 v187, 0x1000, v187
	v_mfma_f32_32x32x16_bf16 v[2:17], v[84:87], v[88:91], v[2:17]
	global_load_dword v132, v187, s[2:3] nt
	global_load_dword v133, v187, s[2:3] offset:128 nt
	v_add_u32_e32 v187, 0x1000, v187
	global_load_dword v134, v187, s[2:3] nt
	global_load_dword v135, v187, s[2:3] offset:128 nt
	v_add_u32_e32 v187, 0x5000, v187
	ds_read_b128 v[76:79], v96 offset:32768
	ds_read_b128 v[80:83], v96 offset:36864
	ds_read_b128 v[84:87], v74 offset:49152
	ds_read_b128 v[88:91], v74 offset:53248
	s_waitcnt lgkmcnt(1)
	v_mfma_f32_32x32x16_bf16 v[34:49], v[76:79], v[84:87], v[34:49]
	global_load_dword v136, v187, s[2:3] nt
	global_load_dword v137, v187, s[2:3] offset:128 nt
	v_add_u32_e32 v187, 0x1000, v187
	global_load_dword v138, v187, s[2:3] nt
	global_load_dword v139, v187, s[2:3] offset:128 nt
	v_add_u32_e32 v187, 0x1000, v187
	v_mfma_f32_32x32x16_bf16 v[18:33], v[80:83], v[84:87], v[18:33]
	global_load_dword v140, v187, s[2:3] nt
	global_load_dword v141, v187, s[2:3] offset:128 nt
	v_add_u32_e32 v187, 0x1000, v187
	global_load_dword v142, v187, s[2:3] nt
	global_load_dword v143, v187, s[2:3] offset:128 nt
	v_add_u32_e32 v187, 0x5000, v187
	s_waitcnt lgkmcnt(0)
	v_mfma_f32_32x32x16_bf16 v[50:65], v[76:79], v[88:91], v[50:65]
	global_load_dword v144, v187, s[2:3] nt
	global_load_dword v145, v187, s[2:3] offset:128 nt
	v_add_u32_e32 v187, 0x1000, v187
	global_load_dword v146, v187, s[2:3] nt
	global_load_dword v147, v187, s[2:3] offset:128 nt
	v_add_u32_e32 v187, 0x1000, v187
	v_mfma_f32_32x32x16_bf16 v[2:17], v[80:83], v[88:91], v[2:17]
	global_load_dword v148, v187, s[2:3] nt
	global_load_dword v149, v187, s[2:3] offset:128 nt
	v_add_u32_e32 v187, 0x1000, v187
	global_load_dword v150, v187, s[2:3] nt
	global_load_dword v151, v187, s[2:3] offset:128 nt
	v_add_u32_e32 v187, 0x5000, v187
	ds_read_b128 v[76:79], v95 offset:49152
	ds_read_b128 v[80:83], v97 offset:32768
	ds_read_b128 v[84:87], v97 offset:36864
	ds_read_b128 v[88:91], v95 offset:53248
	s_waitcnt lgkmcnt(2)
	v_mfma_f32_32x32x16_bf16 v[34:49], v[80:83], v[76:79], v[34:49]
	global_load_dword v152, v187, s[2:3] nt
	global_load_dword v153, v187, s[2:3] offset:128 nt
	v_add_u32_e32 v187, 0x1000, v187
	global_load_dword v154, v187, s[2:3] nt
	global_load_dword v155, v187, s[2:3] offset:128 nt
	v_add_u32_e32 v187, 0x1000, v187
	s_waitcnt lgkmcnt(1)
	v_mfma_f32_32x32x16_bf16 v[18:33], v[84:87], v[76:79], v[18:33]
	global_load_dword v156, v187, s[2:3] nt
	global_load_dword v157, v187, s[2:3] offset:128 nt
	v_add_u32_e32 v187, 0x1000, v187
	global_load_dword v158, v187, s[2:3] nt
	global_load_dword v159, v187, s[2:3] offset:128 nt
	v_add_u32_e32 v187, 0x5000, v187
	s_waitcnt lgkmcnt(0)
	v_mfma_f32_32x32x16_bf16 v[50:65], v[80:83], v[88:91], v[50:65]
	global_load_dword v160, v187, s[2:3] nt
	global_load_dword v161, v187, s[2:3] offset:128 nt
	v_add_u32_e32 v187, 0x1000, v187
	global_load_dword v162, v187, s[2:3] nt
	global_load_dword v163, v187, s[2:3] offset:128 nt
	v_add_u32_e32 v187, 0x1000, v187
	v_mfma_f32_32x32x16_bf16 v[2:17], v[84:87], v[88:91], v[2:17]
	global_load_dword v164, v187, s[2:3] nt
	global_load_dword v165, v187, s[2:3] offset:128 nt
	v_add_u32_e32 v187, 0x1000, v187
	global_load_dword v166, v187, s[2:3] nt
	global_load_dword v167, v187, s[2:3] offset:128 nt
	v_add_u32_e32 v187, 0x5000, v187
	ds_read_b128 v[76:79], v98 offset:49152
	ds_read_b128 v[80:83], v99 offset:32768
	ds_read_b128 v[84:87], v99 offset:36864
	ds_read_b128 v[88:91], v98 offset:53248
	s_waitcnt lgkmcnt(2)
	v_mfma_f32_32x32x16_bf16 v[34:49], v[80:83], v[76:79], v[34:49]
	global_load_dword v168, v187, s[2:3] nt
	global_load_dword v169, v187, s[2:3] offset:128 nt
	v_add_u32_e32 v187, 0x1000, v187
	global_load_dword v170, v187, s[2:3] nt
	global_load_dword v171, v187, s[2:3] offset:128 nt
	v_add_u32_e32 v187, 0x1000, v187
	s_waitcnt lgkmcnt(1)
	v_mfma_f32_32x32x16_bf16 v[18:33], v[84:87], v[76:79], v[18:33]
	global_load_dword v172, v187, s[2:3] nt
	global_load_dword v173, v187, s[2:3] offset:128 nt
	v_add_u32_e32 v187, 0x1000, v187
	global_load_dword v174, v187, s[2:3] nt
	global_load_dword v175, v187, s[2:3] offset:128 nt
	v_add_u32_e32 v187, 0x5000, v187
	s_waitcnt lgkmcnt(0)
	v_mfma_f32_32x32x16_bf16 v[50:65], v[80:83], v[88:91], v[50:65]
	global_load_dword v176, v187, s[2:3] nt
	global_load_dword v177, v187, s[2:3] offset:128 nt
	v_add_u32_e32 v187, 0x1000, v187
	global_load_dword v178, v187, s[2:3] nt
	global_load_dword v179, v187, s[2:3] offset:128 nt
	v_add_u32_e32 v187, 0x1000, v187
	v_mfma_f32_32x32x16_bf16 v[2:17], v[84:87], v[88:91], v[2:17]
	global_load_dword v180, v187, s[2:3] nt
	global_load_dword v181, v187, s[2:3] offset:128 nt
	v_add_u32_e32 v187, 0x1000, v187
	global_load_dword v182, v187, s[2:3] nt
	global_load_dword v183, v187, s[2:3] offset:128 nt
	ds_read_b128 v[76:79], v100 offset:49152
	ds_read_b128 v[80:83], v101 offset:32768
	ds_read_b128 v[84:87], v101 offset:36864
	ds_read_b128 v[88:91], v100 offset:53248
	s_waitcnt lgkmcnt(0)
	s_barrier
; DI void gemm_out(const Params& p, char* lds) {
;     ...
; #pragma unroll
;         for (int tt = 0; tt < 3; ++tt) {
;             const int row = m0 + wm * 48 + tt * 16 + q;
;             const float* xr = row < NTP ? p.x_p + (size_t)row * DM : p.x_s + (size_t)(row - NTP) * DM;
;             float* o = p.out + (size_t)row * DM;
; #pragma unroll
;             for (int ct = 0; ct < 4; ++ct) { const int col = n0 + wn * 64 + ct * 16 + 4 * g; const float4 xv = xres[tt][ct];
;                 const f32x4 w = {xv.x + acc[ct][tt][0], xv.y + acc[ct][tt][1], xv.z + acc[ct][tt][2], xv.w + acc[ct][tt][3]}; __builtin_nontemporal_store(w, (f32x4*)(o + col)); }
;         }
	v_mfma_f32_32x32x16_bf16 v[34:49], v[80:83], v[76:79], v[34:49]
	v_mfma_f32_32x32x16_bf16 v[18:33], v[84:87], v[76:79], v[18:33]
	v_mfma_f32_32x32x16_bf16 v[50:65], v[80:83], v[88:91], v[50:65]
	v_mfma_f32_32x32x16_bf16 v[2:17], v[84:87], v[88:91], v[2:17]
	s_nop 11
	s_waitcnt vmcnt(63)
	v_add_f32_e32 v34, v34, v120
	global_store_dword v188, v34, s[52:53] nt
	s_waitcnt vmcnt(63)
	v_add_f32_e32 v50, v50, v121
	global_store_dword v188, v50, s[52:53] offset:128 nt
	v_add_u32_e32 v188, 0x1000, v188
	s_waitcnt vmcnt(63)
	v_add_f32_e32 v35, v35, v122
	global_store_dword v188, v35, s[52:53] nt
	s_waitcnt vmcnt(63)
	v_add_f32_e32 v51, v51, v123
	global_store_dword v188, v51, s[52:53] offset:128 nt
	v_add_u32_e32 v188, 0x1000, v188
	s_waitcnt vmcnt(63)
	v_add_f32_e32 v36, v36, v124
	global_store_dword v188, v36, s[52:53] nt
	s_waitcnt vmcnt(63)
	v_add_f32_e32 v52, v52, v125
	global_store_dword v188, v52, s[52:53] offset:128 nt
	v_add_u32_e32 v188, 0x1000, v188
	s_waitcnt vmcnt(63)
	v_add_f32_e32 v37, v37, v126
	global_store_dword v188, v37, s[52:53] nt
	s_waitcnt vmcnt(63)
	v_add_f32_e32 v53, v53, v127
	global_store_dword v188, v53, s[52:53] offset:128 nt
	v_add_u32_e32 v188, 0x5000, v188
	s_waitcnt vmcnt(63)
	v_add_f32_e32 v38, v38, v128
	global_store_dword v188, v38, s[52:53] nt
	s_waitcnt vmcnt(63)
	v_add_f32_e32 v54, v54, v129
	global_store_dword v188, v54, s[52:53] offset:128 nt
	v_add_u32_e32 v188, 0x1000, v188
	s_waitcnt vmcnt(63)
	v_add_f32_e32 v39, v39, v130
	global_store_dword v188, v39, s[52:53] nt
	s_waitcnt vmcnt(63)
	v_add_f32_e32 v55, v55, v131
	global_store_dword v188, v55, s[52:53] offset:128 nt
	v_add_u32_e32 v188, 0x1000, v188
	s_waitcnt vmcnt(63)
	v_add_f32_e32 v40, v40, v132
	global_store_dword v188, v40, s[52:53] nt
	s_waitcnt vmcnt(63)
	v_add_f32_e32 v56, v56, v133
	global_store_dword v188, v56, s[52:53] offset:128 nt
	v_add_u32_e32 v188, 0x1000, v188
	s_waitcnt vmcnt(63)
	v_add_f32_e32 v41, v41, v134
	global_store_dword v188, v41, s[52:53] nt
	s_waitcnt vmcnt(63)
	v_add_f32_e32 v57, v57, v135
	global_store_dword v188, v57, s[52:53] offset:128 nt
	v_add_u32_e32 v188, 0x5000, v188
	s_waitcnt vmcnt(63)
	v_add_f32_e32 v42, v42, v136
	global_store_dword v188, v42, s[52:53] nt
	s_waitcnt vmcnt(63)
	v_add_f32_e32 v58, v58, v137
	global_store_dword v188, v58, s[52:53] offset:128 nt
	v_add_u32_e32 v188, 0x1000, v188
	s_waitcnt vmcnt(63)
	v_add_f32_e32 v43, v43, v138
	global_store_dword v188, v43, s[52:53] nt
	s_waitcnt vmcnt(63)
	v_add_f32_e32 v59, v59, v139
	global_store_dword v188, v59, s[52:53] offset:128 nt
	v_add_u32_e32 v188, 0x1000, v188
	s_waitcnt vmcnt(63)
	v_add_f32_e32 v44, v44, v140
	global_store_dword v188, v44, s[52:53] nt
	s_waitcnt vmcnt(63)
	v_add_f32_e32 v60, v60, v141
	global_store_dword v188, v60, s[52:53] offset:128 nt
	v_add_u32_e32 v188, 0x1000, v188
	s_waitcnt vmcnt(63)
	v_add_f32_e32 v45, v45, v142
	global_store_dword v188, v45, s[52:53] nt
	s_waitcnt vmcnt(63)
	v_add_f32_e32 v61, v61, v143
	global_store_dword v188, v61, s[52:53] offset:128 nt
	v_add_u32_e32 v188, 0x5000, v188
	s_waitcnt vmcnt(63)
	v_add_f32_e32 v46, v46, v144
	global_store_dword v188, v46, s[52:53] nt
	s_waitcnt vmcnt(63)
	v_add_f32_e32 v62, v62, v145
	global_store_dword v188, v62, s[52:53] offset:128 nt
	v_add_u32_e32 v188, 0x1000, v188
	s_waitcnt vmcnt(63)
	v_add_f32_e32 v47, v47, v146
	global_store_dword v188, v47, s[52:53] nt
	s_waitcnt vmcnt(63)
	v_add_f32_e32 v63, v63, v147
	global_store_dword v188, v63, s[52:53] offset:128 nt
	v_add_u32_e32 v188, 0x1000, v188
	s_waitcnt vmcnt(63)
	v_add_f32_e32 v48, v48, v148
	global_store_dword v188, v48, s[52:53] nt
	s_waitcnt vmcnt(63)
	v_add_f32_e32 v64, v64, v149
	global_store_dword v188, v64, s[52:53] offset:128 nt
	v_add_u32_e32 v188, 0x1000, v188
	s_waitcnt vmcnt(63)
	v_add_f32_e32 v49, v49, v150
	global_store_dword v188, v49, s[52:53] nt
	s_waitcnt vmcnt(63)
; DI void gemm_out(const Params& p, char* lds) {
;     ...
;     for (int tile = vb; tile < ntile; tile += gridDim.x) {
;     ...
; #pragma unroll
;         for (int tt = 0; tt < 3; ++tt) {
;             const int row = m0 + wm * 48 + tt * 16 + q;
;             const float* xr = row < NTP ? p.x_p + (size_t)row * DM : p.x_s + (size_t)(row - NTP) * DM;
;             float* o = p.out + (size_t)row * DM;
; #pragma unroll
;             for (int ct = 0; ct < 4; ++ct) { const int col = n0 + wn * 64 + ct * 16 + 4 * g; const float4 xv = xres[tt][ct];
;                 const f32x4 w = {xv.x + acc[ct][tt][0], xv.y + acc[ct][tt][1], xv.z + acc[ct][tt][2], xv.w + acc[ct][tt][3]}; __builtin_nontemporal_store(w, (f32x4*)(o + col)); }
;         }
	v_add_f32_e32 v65, v65, v151
	global_store_dword v188, v65, s[52:53] offset:128 nt
	v_add_u32_e32 v188, 0x5000, v188
	s_waitcnt vmcnt(63)
	v_add_f32_e32 v18, v18, v152
	global_store_dword v188, v18, s[52:53] nt
	s_waitcnt vmcnt(63)
	v_add_f32_e32 v2, v2, v153
	global_store_dword v188, v2, s[52:53] offset:128 nt
	v_add_u32_e32 v188, 0x1000, v188
	s_waitcnt vmcnt(63)
	v_add_f32_e32 v19, v19, v154
	global_store_dword v188, v19, s[52:53] nt
	s_waitcnt vmcnt(63)
	v_add_f32_e32 v3, v3, v155
	global_store_dword v188, v3, s[52:53] offset:128 nt
	v_add_u32_e32 v188, 0x1000, v188
	s_waitcnt vmcnt(63)
	v_add_f32_e32 v20, v20, v156
	global_store_dword v188, v20, s[52:53] nt
	s_waitcnt vmcnt(63)
	v_add_f32_e32 v4, v4, v157
	global_store_dword v188, v4, s[52:53] offset:128 nt
	v_add_u32_e32 v188, 0x1000, v188
	s_waitcnt vmcnt(63)
	v_add_f32_e32 v21, v21, v158
	global_store_dword v188, v21, s[52:53] nt
	s_waitcnt vmcnt(63)
	v_add_f32_e32 v5, v5, v159
	global_store_dword v188, v5, s[52:53] offset:128 nt
	v_add_u32_e32 v188, 0x5000, v188
	s_waitcnt vmcnt(63)
	v_add_f32_e32 v22, v22, v160
	global_store_dword v188, v22, s[52:53] nt
	s_waitcnt vmcnt(63)
	v_add_f32_e32 v6, v6, v161
	global_store_dword v188, v6, s[52:53] offset:128 nt
	v_add_u32_e32 v188, 0x1000, v188
	s_waitcnt vmcnt(63)
	v_add_f32_e32 v23, v23, v162
	global_store_dword v188, v23, s[52:53] nt
	s_waitcnt vmcnt(63)
	v_add_f32_e32 v7, v7, v163
	global_store_dword v188, v7, s[52:53] offset:128 nt
	v_add_u32_e32 v188, 0x1000, v188
	s_waitcnt vmcnt(63)
	v_add_f32_e32 v24, v24, v164
	global_store_dword v188, v24, s[52:53] nt
	s_waitcnt vmcnt(63)
	v_add_f32_e32 v8, v8, v165
	global_store_dword v188, v8, s[52:53] offset:128 nt
	v_add_u32_e32 v188, 0x1000, v188
	s_waitcnt vmcnt(63)
	v_add_f32_e32 v25, v25, v166
	global_store_dword v188, v25, s[52:53] nt
	s_waitcnt vmcnt(63)
	v_add_f32_e32 v9, v9, v167
	global_store_dword v188, v9, s[52:53] offset:128 nt
	v_add_u32_e32 v188, 0x5000, v188
	s_waitcnt vmcnt(63)
	v_add_f32_e32 v26, v26, v168
	global_store_dword v188, v26, s[52:53] nt
	s_waitcnt vmcnt(63)
	v_add_f32_e32 v10, v10, v169
	global_store_dword v188, v10, s[52:53] offset:128 nt
	v_add_u32_e32 v188, 0x1000, v188
	s_waitcnt vmcnt(63)
	v_add_f32_e32 v27, v27, v170
	global_store_dword v188, v27, s[52:53] nt
	s_waitcnt vmcnt(63)
	v_add_f32_e32 v11, v11, v171
	global_store_dword v188, v11, s[52:53] offset:128 nt
	v_add_u32_e32 v188, 0x1000, v188
	s_waitcnt vmcnt(63)
	v_add_f32_e32 v28, v28, v172
	global_store_dword v188, v28, s[52:53] nt
	s_waitcnt vmcnt(63)
	v_add_f32_e32 v12, v12, v173
	global_store_dword v188, v12, s[52:53] offset:128 nt
	v_add_u32_e32 v188, 0x1000, v188
	s_waitcnt vmcnt(63)
	v_add_f32_e32 v29, v29, v174
	global_store_dword v188, v29, s[52:53] nt
	s_waitcnt vmcnt(63)
	v_add_f32_e32 v13, v13, v175
	global_store_dword v188, v13, s[52:53] offset:128 nt
	v_add_u32_e32 v188, 0x5000, v188
	s_waitcnt vmcnt(63)
	v_add_f32_e32 v30, v30, v176
	global_store_dword v188, v30, s[52:53] nt
	s_waitcnt vmcnt(63)
	v_add_f32_e32 v14, v14, v177
	global_store_dword v188, v14, s[52:53] offset:128 nt
	v_add_u32_e32 v188, 0x1000, v188
	s_waitcnt vmcnt(63)
	v_add_f32_e32 v31, v31, v178
	global_store_dword v188, v31, s[52:53] nt
	s_waitcnt vmcnt(63)
	v_add_f32_e32 v15, v15, v179
	global_store_dword v188, v15, s[52:53] offset:128 nt
	v_add_u32_e32 v188, 0x1000, v188
	s_waitcnt vmcnt(63)
	v_add_f32_e32 v32, v32, v180
	global_store_dword v188, v32, s[52:53] nt
	s_waitcnt vmcnt(63)
	v_add_f32_e32 v16, v16, v181
	global_store_dword v188, v16, s[52:53] offset:128 nt
	v_add_u32_e32 v188, 0x1000, v188
	s_waitcnt vmcnt(63)
	v_add_f32_e32 v33, v33, v182
	global_store_dword v188, v33, s[52:53] nt
	s_waitcnt vmcnt(63)
	v_add_f32_e32 v17, v17, v183
	global_store_dword v188, v17, s[52:53] offset:128 nt
	v_readlane_b32 s95, v236, 8
	s_cmpk_lt_i32 s33, 0x420
	s_mov_b32 s0, s88
	s_mov_b32 s82, s86
	s_cbranch_scc1 .Lo_tile
